# mixer v2: conv rows in flight before the pooling stage + next item's rows prefetched (cross-item), GN temps in dead weight regs
# speedup vs baseline: 1.0097x; 1.0038x over previous
;     __device__ __forceinline__ bf16_t* U() const { return (bf16_t*)(ws + WS_U); }
;     __device__ __forceinline__ bf16_t* P() const { return (bf16_t*)(ws + WS_P); }
;     __device__ __forceinline__ bf16_t* MIX() const { return (bf16_t*)(ws + WS_MIX); }
; __device__ __forceinline__ void mixer_prompt_run(const Args& p, int run, int c2) {
;     const int b = run >> 7, t0 = (run & 127) * 16;
;     const unsigned* U32 = (const unsigned*)p.U(); const unsigned* P32 = (const unsigned*)p.P(); unsigned* M32 = (unsigned*)p.MIX();
;     const size_t rowb = (size_t)b * SEQ;
;     {
;         unsigned pin[31];
; #pragma unroll
;         for (int i = 0; i < 31; ++i) { const int t = t0 - 15 + i; const unsigned v = P32[(rowb + (t >= 0 ? t : 0)) * 256 + c2]; pin[i] = (t >= 0) ? v : 0u; }
;         const int gi = __builtin_amdgcn_readfirstlane(c2 >> 6);
;         unsigned* dst = M32 + (rowb + t0) * 512 + 256 + c2;
;         if (gi == 0) pool_prompt_w<2>(pin, t0, dst); else if (gi == 1) pool_prompt_w<4>(pin, t0, dst); else if (gi == 2) pool_prompt_w<8>(pin, t0, dst); else pool_prompt_w<16>(pin, t0, dst);
;     }
;     asm volatile("" ::: "memory");
;     {
;         f32x2v w[31];
; #pragma unroll
;         for (int j = 0; j < 31; ++j) w[j] = *(const f32x2v*)(p.conv_w() + j * 512 + 2 * c2);
;         const f32x2v cb = *(const f32x2v*)(p.conv_b() + 2 * c2);
;         const f32x2v gg = *(const f32x2v*)(p.gn_g() + 2 * c2), gb = *(const f32x2v*)(p.gn_b() + 2 * c2);
.LBB0_600:
	v_and_b32_e32 v164, 0xff, v192
	s_lshr_b32 s41, s0, 8
	s_movk_i32 s0, 0x7f
	v_lshlrev_b32_e32 v74, 3, v164
	v_mov_b32_e32 v75, 0
	v_cmp_lt_u32_e64 s[4:5], s0, v164
	s_waitcnt lgkmcnt(0)
	v_lshl_add_u64 v[2:3], s[62:63], 0, v[74:75]
	s_mov_b64 s[0:1], 0x1000
	v_lshl_add_u64 v[4:5], v[2:3], 0, s[0:1]
	s_mov_b64 s[0:1], 0x1800
	v_lshl_add_u64 v[6:7], v[2:3], 0, s[0:1]
	s_mov_b64 s[0:1], 0x2000
	s_waitcnt vmcnt(0)
	v_lshl_add_u64 v[8:9], v[2:3], 0, s[0:1]
	s_mov_b64 s[0:1], 0x2800
	v_lshl_add_u64 v[10:11], v[2:3], 0, s[0:1]
	s_mov_b64 s[0:1], 0x3000
	v_lshl_add_u64 v[12:13], v[2:3], 0, s[0:1]
	s_mov_b64 s[0:1], 0x3800
	v_lshl_add_u64 v[14:15], v[2:3], 0, s[0:1]
	s_mov_b64 s[0:1], 0x4000
	v_lshl_add_u64 v[16:17], v[2:3], 0, s[0:1]
	s_mov_b64 s[0:1], 0x4800
	v_lshl_add_u64 v[18:19], v[2:3], 0, s[0:1]
	s_mov_b64 s[0:1], 0x5000
	v_lshl_add_u64 v[20:21], v[2:3], 0, s[0:1]
	s_mov_b64 s[0:1], 0x5800
	v_lshl_add_u64 v[22:23], v[2:3], 0, s[0:1]
	s_mov_b64 s[0:1], 0x6000
	v_lshl_add_u64 v[24:25], v[2:3], 0, s[0:1]
	s_mov_b64 s[0:1], 0x6800
	v_lshl_add_u64 v[26:27], v[2:3], 0, s[0:1]
	s_mov_b64 s[0:1], 0x7000
	v_lshl_add_u64 v[28:29], v[2:3], 0, s[0:1]
	s_mov_b64 s[0:1], 0x7800
	v_lshl_add_u64 v[30:31], v[2:3], 0, s[0:1]
	s_mov_b64 s[0:1], 0x8000
	v_lshl_add_u64 v[32:33], v[2:3], 0, s[0:1]
	s_mov_b64 s[0:1], 0x8800
	v_lshl_add_u64 v[34:35], v[2:3], 0, s[0:1]
	s_mov_b64 s[0:1], 0x9000
	v_lshl_add_u64 v[36:37], v[2:3], 0, s[0:1]
	s_mov_b64 s[0:1], 0x9800
	v_lshl_add_u64 v[38:39], v[2:3], 0, s[0:1]
	s_mov_b64 s[0:1], 0xa000
	v_lshl_add_u64 v[40:41], v[2:3], 0, s[0:1]
	s_mov_b64 s[0:1], 0xa800
	v_lshl_add_u64 v[42:43], v[2:3], 0, s[0:1]
	s_mov_b64 s[0:1], 0xb000
	v_lshl_add_u64 v[44:45], v[2:3], 0, s[0:1]
	s_mov_b64 s[0:1], 0xb800
	v_writelane_b32 v242, s92, 36
	v_lshl_add_u64 v[46:47], v[2:3], 0, s[0:1]
	s_mov_b64 s[0:1], 0xc000
	v_writelane_b32 v242, s93, 37
	v_lshl_add_u64 v[48:49], v[2:3], 0, s[0:1]
	s_mov_b64 s[0:1], 0xc800
	v_writelane_b32 v242, s88, 38
	v_lshl_add_u64 v[50:51], v[2:3], 0, s[0:1]
	s_mov_b64 s[0:1], 0xd000
	v_writelane_b32 v242, s89, 39
	v_lshl_add_u64 v[52:53], v[2:3], 0, s[0:1]
	s_mov_b64 s[0:1], 0xd800
	v_writelane_b32 v242, s90, 40
	v_lshl_add_u64 v[54:55], v[2:3], 0, s[0:1]
	s_mov_b64 s[0:1], 0xe000
	v_writelane_b32 v242, s91, 41
	v_lshl_add_u64 v[56:57], v[2:3], 0, s[0:1]
	s_mov_b64 s[0:1], 0xe800
	v_lshl_add_u64 v[58:59], v[2:3], 0, s[0:1]
	s_mov_b64 s[0:1], 0xf000
	v_lshlrev_b32_e32 v64, 2, v164
	v_mov_b32_e32 v65, v75
	v_readlane_b32 s8, v242, 19
	v_bfe_u32 v1, v192, 6, 2
	v_lshl_add_u64 v[60:61], v[2:3], 0, s[0:1]
	v_lshl_add_u64 v[76:77], s[58:59], 0, v[64:65]
	s_mov_b64 s[0:1], 0x4d00000
	v_readlane_b32 s12, v242, 23
	v_readlane_b32 s13, v242, 24
	v_readlane_b32 s14, v242, 25
	v_readlane_b32 s15, v242, 26
	v_readlane_b32 s16, v242, 27
	v_readlane_b32 s17, v242, 28
	v_lshlrev_b32_e64 v0, v1, 2
	v_lshl_add_u64 v[64:65], v[76:77], 0, s[0:1]
	v_readlane_b32 s18, v242, 29
	v_readlane_b32 s19, v242, 30
	v_readlane_b32 s20, v242, 31
	v_readlane_b32 s21, v242, 32
	s_mov_b64 s[12:13], s[16:17]
	s_mov_b64 s[0:1], 0x6e00000
	v_cvt_f32_ubyte0_e32 v0, v0
	s_mov_b64 s[14:15], s[18:19]
	s_mov_b64 s[16:17], s[20:21]
	v_lshl_add_u64 v[72:73], v[76:77], 0, s[0:1]
	s_mov_b64 s[0:1], 0x5d80000
	v_mbcnt_lo_u32_b32 v78, -1, 0
	s_add_i32 s49, s41, 0xfffffc00
	v_cmp_gt_u32_e64 s[2:3], 64, v164
	v_cmp_eq_u32_e64 s[6:7], 3, v1
	v_lshl_add_u64 v[62:63], s[64:65], 0, v[74:75]
	v_lshl_add_u64 v[66:67], s[14:15], 0, v[74:75]
	v_lshl_add_u64 v[68:69], s[66:67], 0, v[74:75]
	v_lshl_add_u64 v[70:71], s[68:69], 0, v[74:75]
	v_lshl_add_u64 v[74:75], s[16:17], 0, v[74:75]
	v_lshl_add_u64 v[76:77], v[76:77], 0, s[0:1]
	v_mov_b32_e32 v1, v0
	s_mov_b32 s45, 0
	s_movk_i32 s61, 0x1000
	s_movk_i32 s90, 0x2000
	s_movk_i32 s91, 0x3000
	s_movk_i32 s82, 0x4000
	s_movk_i32 s83, 0x5000
	s_movk_i32 s95, 0x6000
	s_movk_i32 s92, 0x7000
	s_mov_b32 s48, 0x3c800000
	s_mov_b32 s60, 0x3727c5ac
	s_mov_b32 s93, 0x800000
	v_mbcnt_hi_u32_b32 v165, -1, v78
	v_mov_b32_e32 v166, 0xf000
	v_mov_b32_e32 v167, 0x7800
	v_readlane_b32 s9, v242, 20
	v_readlane_b32 s10, v242, 21
	v_readlane_b32 s11, v242, 22
	v_readlane_b32 s22, v242, 33
	v_readlane_b32 s23, v242, 34
	s_mov_b32 s80, 0
	s_branch .LBB0_602

; __device__ __forceinline__ f32x2v bf2(unsigned v) { return (f32x2v){bflo(v), bfhi(v)}; }
; __device__ __forceinline__ void mixer_prompt_run(const Args& p, int run, int c2) {
;     ...
;     const size_t rowb = (size_t)b * SEQ;
;     {
;         unsigned pin[31];
; #pragma unroll
;         for (int i = 0; i < 31; ++i) { const int t = t0 - 15 + i; const unsigned v = P32[(rowb + (t >= 0 ? t : 0)) * 256 + c2]; pin[i] = (t >= 0) ? v : 0u; }
;         const int gi = __builtin_amdgcn_readfirstlane(c2 >> 6);
;         unsigned* dst = M32 + (rowb + t0) * 512 + 256 + c2;
;         if (gi == 0) pool_prompt_w<2>(pin, t0, dst); else if (gi == 1) pool_prompt_w<4>(pin, t0, dst); else if (gi == 2) pool_prompt_w<8>(pin, t0, dst); else pool_prompt_w<16>(pin, t0, dst);
;     ...
;             for (int i = 0; i < 38; ++i) {
;                 const int ti = t0 + 8 * hh - 30 + i; unsigned v = U32[(rowb + (ti >= 0 ? ti : 0)) * 256 + c2]; v = (ti >= 0) ? v : 0u; const f32x2v x = bf2(v);
.LBB0_604:
	s_andn2_b64 vcc, exec, s[0:1]
	s_cbranch_vccnz .LBB0_601
	s_add_i32 s62, s20, s41
	v_readfirstlane_b32 s75, v192
	v_lshlrev_b32_e32 v105, 2, v164
	s_lshr_b32 s63, s62, 7
	s_and_b32 s64, s62, 0x7f
	s_lshl_b32 s64, s64, 4
	s_lshl_b32 s63, s63, 11
	s_add_i32 s63, s63, s64
	s_lshr_b32 s75, s75, 6
	s_and_b32 s75, s75, 3
	s_sub_i32 s1, s63, 30
	s_lshl_b32 s65, s1, 10
	s_ashr_i32 s0, s65, 31
	s_add_u32 s66, s58, s65
	s_addc_u32 s67, s59, s0
	s_add_u32 s66, s66, 0x4d01000
	s_addc_u32 s67, s67, 0
	s_cmp_eq_u32 s80, 1
	s_cbranch_scc1 .Lmx_pref
	s_sub_i32 s1, s63, 15
	s_lshl_b32 s65, s1, 10
	s_ashr_i32 s0, s65, 31
	s_add_u32 s68, s58, s65
	s_addc_u32 s69, s59, s0
	s_add_u32 s68, s68, 0x5d81000
	s_addc_u32 s69, s69, 0
	global_load_dword v172, v105, s[68:69] offset:-4096
	global_load_dword v173, v105, s[68:69] offset:-3072
	global_load_dword v174, v105, s[68:69] offset:-2048
	global_load_dword v175, v105, s[68:69] offset:-1024
	global_load_dword v176, v105, s[68:69] offset:0
	global_load_dword v177, v105, s[68:69] offset:1024
	global_load_dword v178, v105, s[68:69] offset:2048
	global_load_dword v179, v105, s[68:69] offset:3072
	s_add_u32 s68, s68, 0x2000
	s_addc_u32 s69, s69, 0
	global_load_dword v180, v105, s[68:69] offset:-4096
	global_load_dword v181, v105, s[68:69] offset:-3072
	global_load_dword v182, v105, s[68:69] offset:-2048
	global_load_dword v183, v105, s[68:69] offset:-1024
	global_load_dword v184, v105, s[68:69] offset:0
	global_load_dword v185, v105, s[68:69] offset:1024
	global_load_dword v186, v105, s[68:69] offset:2048
	global_load_dword v187, v105, s[68:69] offset:3072
	s_add_u32 s68, s68, 0x2000
	s_addc_u32 s69, s69, 0
	global_load_dword v188, v105, s[68:69] offset:-4096
	global_load_dword v189, v105, s[68:69] offset:-3072
	global_load_dword v190, v105, s[68:69] offset:-2048
	global_load_dword v191, v105, s[68:69] offset:-1024
	global_load_dword v78, v105, s[68:69] offset:0
	global_load_dword v79, v105, s[68:69] offset:1024
	global_load_dword v80, v105, s[68:69] offset:2048
	global_load_dword v81, v105, s[68:69] offset:3072
	s_add_u32 s68, s68, 0x2000
	s_addc_u32 s69, s69, 0
	global_load_dword v82, v105, s[68:69] offset:-4096
	global_load_dword v83, v105, s[68:69] offset:-3072
	global_load_dword v84, v105, s[68:69] offset:-2048
	global_load_dword v85, v105, s[68:69] offset:-1024
	global_load_dword v86, v105, s[68:69] offset:0
	global_load_dword v87, v105, s[68:69] offset:1024
	global_load_dword v88, v105, s[68:69] offset:2048
	s_waitcnt vmcnt(31)
	global_load_dword v193, v105, s[66:67] offset:-4096
	global_load_dword v194, v105, s[66:67] offset:-3072
	global_load_dword v195, v105, s[66:67] offset:-2048
	global_load_dword v196, v105, s[66:67] offset:-1024
	global_load_dword v197, v105, s[66:67] offset:0
	global_load_dword v198, v105, s[66:67] offset:1024
	global_load_dword v199, v105, s[66:67] offset:2048
	global_load_dword v200, v105, s[66:67] offset:3072
	s_add_u32 s66, s66, 0x2000
	s_addc_u32 s67, s67, 0
	global_load_dword v201, v105, s[66:67] offset:-4096
	global_load_dword v202, v105, s[66:67] offset:-3072
	global_load_dword v203, v105, s[66:67] offset:-2048
	global_load_dword v204, v105, s[66:67] offset:-1024
	global_load_dword v205, v105, s[66:67] offset:0
	global_load_dword v206, v105, s[66:67] offset:1024
	global_load_dword v207, v105, s[66:67] offset:2048
	global_load_dword v208, v105, s[66:67] offset:3072
	s_branch .Lmx_join
.Lmx_pref:
	s_waitcnt vmcnt(47)
	s_add_u32 s66, s66, 0x2000
	s_addc_u32 s67, s67, 0
.Lmx_join:
	s_add_u32 s66, s66, 0x2000
	s_addc_u32 s67, s67, 0
	global_load_dword v209, v105, s[66:67] offset:-4096
	global_load_dword v210, v105, s[66:67] offset:-3072
	global_load_dword v211, v105, s[66:67] offset:-2048
	global_load_dword v212, v105, s[66:67] offset:-1024
	global_load_dword v213, v105, s[66:67] offset:0
	global_load_dword v214, v105, s[66:67] offset:1024
	global_load_dword v215, v105, s[66:67] offset:2048
	global_load_dword v216, v105, s[66:67] offset:3072
	s_add_u32 s66, s66, 0x2000
	s_addc_u32 s67, s67, 0
	global_load_dword v217, v105, s[66:67] offset:-4096
	global_load_dword v218, v105, s[66:67] offset:-3072
	global_load_dword v219, v105, s[66:67] offset:-2048
	global_load_dword v220, v105, s[66:67] offset:-1024
	global_load_dword v221, v105, s[66:67] offset:0
	global_load_dword v222, v105, s[66:67] offset:1024
	global_load_dword v223, v105, s[66:67] offset:2048
	global_load_dword v224, v105, s[66:67] offset:3072
	s_mov_b32 s80, 0
	s_lshl_b32 s65, s63, 11
	s_ashr_i32 s0, s65, 31
	s_add_u32 s70, s58, s65
	s_addc_u32 s71, s59, s0
	s_add_u32 s70, s70, 0x6e01000
	s_addc_u32 s71, s71, 0
	s_mov_b32 s76, s70
	s_mov_b32 s77, s71
	s_lshl_b32 s74, 2, s75
	s_sub_i32 s72, 126, s75
	s_lshl_b32 s72, s72, 23
	s_mov_b32 s73, s72
	s_cmp_lt_i32 s64, 32
	s_cselect_b64 vcc, -1, 0
	s_waitcnt vmcnt(32)
	s_cmp_eq_u32 s64, 0
	s_cbranch_scc0 .Lmx_pnz
	v_mov_b32_e32 v172, 0
	v_mov_b32_e32 v173, 0
	v_mov_b32_e32 v174, 0
	v_mov_b32_e32 v175, 0
	v_mov_b32_e32 v176, 0
	v_mov_b32_e32 v177, 0
	v_mov_b32_e32 v178, 0
	v_mov_b32_e32 v179, 0
	v_mov_b32_e32 v180, 0
	v_mov_b32_e32 v181, 0
	v_mov_b32_e32 v182, 0
	v_mov_b32_e32 v183, 0
	v_mov_b32_e32 v184, 0
	v_mov_b32_e32 v185, 0
	v_mov_b32_e32 v186, 0
; __device__ __forceinline__ unsigned pk2(float lo, float hi) { f32x2v v = {lo, hi}; b16x2v b = __builtin_convertvector(v, b16x2v); return __builtin_bit_cast(unsigned, b); }
; __device__ __forceinline__ f32x2v bf2(unsigned v) { return (f32x2v){bflo(v), bfhi(v)}; }
; template <int W>
; __device__ __forceinline__ void pool_prompt_w(const unsigned (&pin)[31], int t0, unsigned* dst  ) {
;     f32x2v s = {0.f, 0.f};
; #pragma unroll
;     for (int i = 0; i < W; ++i) s = s + bf2(pin[15 - i]);
; #pragma unroll
;     for (int t = 0; t < 16; ++t) {
;         if (t > 0) s = s + (bf2(pin[15 + t]) - bf2(pin[15 + t - W]));
;         const float cnt = (float)min(t0 + t + 1, W); const f32x2v cur = bf2(pin[15 + t]);
;         dst[(size_t)t * 512] = pk2(s.x / cnt - cur.x, s.y / cnt - cur.y);
; __device__ __forceinline__ void mixer_prompt_run(const Args& p, int run, int c2) {
;     ...
;         f32x2v w[31];
; #pragma unroll
;         for (int j = 0; j < 31; ++j) w[j] = *(const f32x2v*)(p.conv_w() + j * 512 + 2 * c2);
;         const f32x2v cb = *(const f32x2v*)(p.conv_b() + 2 * c2);
;         const f32x2v gg = *(const f32x2v*)(p.gn_g() + 2 * c2), gb = *(const f32x2v*)(p.gn_b() + 2 * c2);
.Lmx_pnz:
	s_waitcnt vmcnt(14)
	global_load_dwordx2 v[106:107], v[2:3], off
	global_load_dwordx2 v[108:109], v[2:3], off offset:2048
	global_load_dwordx2 v[110:111], v[4:5], off
	global_load_dwordx2 v[112:113], v[6:7], off
	global_load_dwordx2 v[114:115], v[8:9], off
	global_load_dwordx2 v[116:117], v[10:11], off
	global_load_dwordx2 v[118:119], v[12:13], off
	global_load_dwordx2 v[120:121], v[14:15], off
	global_load_dwordx2 v[122:123], v[16:17], off
	global_load_dwordx2 v[124:125], v[18:19], off
	global_load_dwordx2 v[126:127], v[20:21], off
	global_load_dwordx2 v[128:129], v[22:23], off
	global_load_dwordx2 v[130:131], v[24:25], off
	global_load_dwordx2 v[132:133], v[26:27], off
	global_load_dwordx2 v[134:135], v[28:29], off
	global_load_dwordx2 v[136:137], v[30:31], off
	global_load_dwordx2 v[138:139], v[32:33], off
	global_load_dwordx2 v[140:141], v[34:35], off
	global_load_dwordx2 v[142:143], v[36:37], off
	global_load_dwordx2 v[144:145], v[38:39], off
	global_load_dwordx2 v[146:147], v[40:41], off
	global_load_dwordx2 v[148:149], v[42:43], off
	global_load_dwordx2 v[150:151], v[44:45], off
	global_load_dwordx2 v[152:153], v[46:47], off
	global_load_dwordx2 v[154:155], v[48:49], off
	global_load_dwordx2 v[156:157], v[50:51], off
	global_load_dwordx2 v[158:159], v[52:53], off
	global_load_dwordx2 v[160:161], v[54:55], off
	global_load_dwordx2 v[162:163], v[56:57], off
	global_load_dwordx2 v[168:169], v[58:59], off
	global_load_dwordx2 v[170:171], v[60:61], off
	global_load_dwordx2 v[90:91], v[62:63], off
	global_load_dwordx2 v[92:93], v[68:69], off
	global_load_dwordx2 v[94:95], v[70:71], off
	s_add_u32 s66, s66, 0x2000
	s_addc_u32 s67, s67, 0
	global_load_dword v225, v105, s[66:67] offset:-4096
	global_load_dword v226, v105, s[66:67] offset:-3072
	global_load_dword v227, v105, s[66:67] offset:-2048
	global_load_dword v228, v105, s[66:67] offset:-1024
	global_load_dword v229, v105, s[66:67] offset:0
	global_load_dword v230, v105, s[66:67] offset:1024
	global_load_dword v231, v105, s[66:67] offset:2048
	global_load_dword v232, v105, s[66:67] offset:3072
	s_add_u32 s66, s66, 0x2000
	s_addc_u32 s67, s67, 0
	global_load_dword v233, v105, s[66:67] offset:-4096
	global_load_dword v234, v105, s[66:67] offset:-3072
	global_load_dword v235, v105, s[66:67] offset:-2048
	global_load_dword v236, v105, s[66:67] offset:-1024
	global_load_dword v237, v105, s[66:67] offset:0
	global_load_dword v238, v105, s[66:67] offset:1024
	s_cmp_eq_u32 s75, 0
	s_cbranch_scc1 .Lmx_pool0
	s_cmp_eq_u32 s75, 1
	s_cbranch_scc1 .Lmx_pool1
	s_cmp_eq_u32 s75, 2
	s_cbranch_scc1 .Lmx_pool2
	s_branch .Lmx_pool3
.Lmx_pool0:
	v_lshlrev_b32_e32 v100, 16, v187
	v_and_b32_e32 v101, 0xffff0000, v187
	v_lshlrev_b32_e32 v96, 16, v186
	v_and_b32_e32 v97, 0xffff0000, v186
	v_pk_add_f32 v[100:101], v[100:101], v[96:97]
	v_lshlrev_b32_e32 v102, 16, v187
	v_and_b32_e32 v103, 0xffff0000, v187
	s_cmp_eq_u32 s64, 0
	s_cbranch_scc1 .Lmx_ps0_0
	v_pk_mul_f32 v[98:99], v[100:101], s[72:73] op_sel_hi:[1,0]
.Lmx_pb0_0:
	v_pk_add_f32 v[98:99], v[98:99], v[102:103] neg_lo:[0,1] neg_hi:[0,1]
	v_cvt_pk_bf16_f32 v104, v98, v99
	s_waitcnt vmcnt(47)
	global_store_dword v105, v104, s[76:77] offset:-3072
	v_lshlrev_b32_e32 v102, 16, v188
	v_and_b32_e32 v103, 0xffff0000, v188
	v_lshlrev_b32_e32 v96, 16, v186
	v_and_b32_e32 v97, 0xffff0000, v186
	v_pk_add_f32 v[96:97], v[102:103], v[96:97] neg_lo:[0,1] neg_hi:[0,1]
	v_pk_add_f32 v[100:101], v[100:101], v[96:97]
	v_pk_mul_f32 v[98:99], v[100:101], s[72:73] op_sel_hi:[1,0]
	v_pk_add_f32 v[98:99], v[98:99], v[102:103] neg_lo:[0,1] neg_hi:[0,1]
	v_cvt_pk_bf16_f32 v239, v98, v99
	global_store_dword v105, v239, s[76:77] offset:-1024
	v_lshlrev_b32_e32 v102, 16, v189
	v_and_b32_e32 v103, 0xffff0000, v189
	v_lshlrev_b32_e32 v96, 16, v187
	v_and_b32_e32 v97, 0xffff0000, v187
	v_pk_add_f32 v[96:97], v[102:103], v[96:97] neg_lo:[0,1] neg_hi:[0,1]
	v_pk_add_f32 v[100:101], v[100:101], v[96:97]
	v_pk_mul_f32 v[98:99], v[100:101], s[72:73] op_sel_hi:[1,0]
	v_pk_add_f32 v[98:99], v[98:99], v[102:103] neg_lo:[0,1] neg_hi:[0,1]
	v_cvt_pk_bf16_f32 v240, v98, v99
	global_store_dword v105, v240, s[76:77] offset:1024
	v_lshlrev_b32_e32 v102, 16, v190
	v_and_b32_e32 v103, 0xffff0000, v190
	v_lshlrev_b32_e32 v96, 16, v188
	v_and_b32_e32 v97, 0xffff0000, v188
	v_pk_add_f32 v[96:97], v[102:103], v[96:97] neg_lo:[0,1] neg_hi:[0,1]
	v_pk_add_f32 v[100:101], v[100:101], v[96:97]
	v_pk_mul_f32 v[98:99], v[100:101], s[72:73] op_sel_hi:[1,0]
	v_pk_add_f32 v[98:99], v[98:99], v[102:103] neg_lo:[0,1] neg_hi:[0,1]
	v_cvt_pk_bf16_f32 v241, v98, v99
	global_store_dword v105, v241, s[76:77] offset:3072
	v_lshlrev_b32_e32 v102, 16, v191
	v_and_b32_e32 v103, 0xffff0000, v191
	v_lshlrev_b32_e32 v96, 16, v189
	v_and_b32_e32 v97, 0xffff0000, v189
	v_pk_add_f32 v[96:97], v[102:103], v[96:97] neg_lo:[0,1] neg_hi:[0,1]
	v_pk_add_f32 v[100:101], v[100:101], v[96:97]
	v_pk_mul_f32 v[98:99], v[100:101], s[72:73] op_sel_hi:[1,0]
	v_pk_add_f32 v[98:99], v[98:99], v[102:103] neg_lo:[0,1] neg_hi:[0,1]
	v_cvt_pk_bf16_f32 v104, v98, v99
	s_add_u32 s76, s76, 0x2000
	s_addc_u32 s77, s77, 0
	global_store_dword v105, v104, s[76:77] offset:-3072
	v_lshlrev_b32_e32 v102, 16, v78
	v_and_b32_e32 v103, 0xffff0000, v78
	v_lshlrev_b32_e32 v96, 16, v190
	v_and_b32_e32 v97, 0xffff0000, v190
	v_pk_add_f32 v[96:97], v[102:103], v[96:97] neg_lo:[0,1] neg_hi:[0,1]
	v_pk_add_f32 v[100:101], v[100:101], v[96:97]
	v_pk_mul_f32 v[98:99], v[100:101], s[72:73] op_sel_hi:[1,0]
	v_pk_add_f32 v[98:99], v[98:99], v[102:103] neg_lo:[0,1] neg_hi:[0,1]
	v_cvt_pk_bf16_f32 v239, v98, v99
	global_store_dword v105, v239, s[76:77] offset:-1024
; __device__ __forceinline__ unsigned pk2(float lo, float hi) { f32x2v v = {lo, hi}; b16x2v b = __builtin_convertvector(v, b16x2v); return __builtin_bit_cast(unsigned, b); }
; __device__ __forceinline__ f32x2v bf2(unsigned v) { return (f32x2v){bflo(v), bfhi(v)}; }
; template <int W>
; __device__ __forceinline__ void pool_prompt_w(const unsigned (&pin)[31], int t0, unsigned* dst  ) {
;     f32x2v s = {0.f, 0.f};
; #pragma unroll
;     for (int i = 0; i < W; ++i) s = s + bf2(pin[15 - i]);
; #pragma unroll
;     for (int t = 0; t < 16; ++t) {
;         if (t > 0) s = s + (bf2(pin[15 + t]) - bf2(pin[15 + t - W]));
;         const float cnt = (float)min(t0 + t + 1, W); const f32x2v cur = bf2(pin[15 + t]);
;         dst[(size_t)t * 512] = pk2(s.x / cnt - cur.x, s.y / cnt - cur.y);
	v_lshlrev_b32_e32 v102, 16, v79
	v_and_b32_e32 v103, 0xffff0000, v79
	v_lshlrev_b32_e32 v96, 16, v191
	v_and_b32_e32 v97, 0xffff0000, v191
	v_pk_add_f32 v[96:97], v[102:103], v[96:97] neg_lo:[0,1] neg_hi:[0,1]
	v_pk_add_f32 v[100:101], v[100:101], v[96:97]
	v_pk_mul_f32 v[98:99], v[100:101], s[72:73] op_sel_hi:[1,0]
	v_pk_add_f32 v[98:99], v[98:99], v[102:103] neg_lo:[0,1] neg_hi:[0,1]
	v_cvt_pk_bf16_f32 v240, v98, v99
	global_store_dword v105, v240, s[76:77] offset:1024
	v_lshlrev_b32_e32 v102, 16, v80
	v_and_b32_e32 v103, 0xffff0000, v80
	v_lshlrev_b32_e32 v96, 16, v78
	v_and_b32_e32 v97, 0xffff0000, v78
	v_pk_add_f32 v[96:97], v[102:103], v[96:97] neg_lo:[0,1] neg_hi:[0,1]
	v_pk_add_f32 v[100:101], v[100:101], v[96:97]
	v_pk_mul_f32 v[98:99], v[100:101], s[72:73] op_sel_hi:[1,0]
	v_pk_add_f32 v[98:99], v[98:99], v[102:103] neg_lo:[0,1] neg_hi:[0,1]
	v_cvt_pk_bf16_f32 v241, v98, v99
	global_store_dword v105, v241, s[76:77] offset:3072
	v_lshlrev_b32_e32 v102, 16, v81
	v_and_b32_e32 v103, 0xffff0000, v81
	v_lshlrev_b32_e32 v96, 16, v79
	v_and_b32_e32 v97, 0xffff0000, v79
	v_pk_add_f32 v[96:97], v[102:103], v[96:97] neg_lo:[0,1] neg_hi:[0,1]
	v_pk_add_f32 v[100:101], v[100:101], v[96:97]
	v_pk_mul_f32 v[98:99], v[100:101], s[72:73] op_sel_hi:[1,0]
	v_pk_add_f32 v[98:99], v[98:99], v[102:103] neg_lo:[0,1] neg_hi:[0,1]
	v_cvt_pk_bf16_f32 v104, v98, v99
	s_add_u32 s76, s76, 0x2000
	s_addc_u32 s77, s77, 0
	global_store_dword v105, v104, s[76:77] offset:-3072
	v_lshlrev_b32_e32 v102, 16, v82
	v_and_b32_e32 v103, 0xffff0000, v82
	v_lshlrev_b32_e32 v96, 16, v80
	v_and_b32_e32 v97, 0xffff0000, v80
	v_pk_add_f32 v[96:97], v[102:103], v[96:97] neg_lo:[0,1] neg_hi:[0,1]
	v_pk_add_f32 v[100:101], v[100:101], v[96:97]
	v_pk_mul_f32 v[98:99], v[100:101], s[72:73] op_sel_hi:[1,0]
	v_pk_add_f32 v[98:99], v[98:99], v[102:103] neg_lo:[0,1] neg_hi:[0,1]
	v_cvt_pk_bf16_f32 v239, v98, v99
	global_store_dword v105, v239, s[76:77] offset:-1024
	v_lshlrev_b32_e32 v102, 16, v83
	v_and_b32_e32 v103, 0xffff0000, v83
	v_lshlrev_b32_e32 v96, 16, v81
	v_and_b32_e32 v97, 0xffff0000, v81
	v_pk_add_f32 v[96:97], v[102:103], v[96:97] neg_lo:[0,1] neg_hi:[0,1]
	v_pk_add_f32 v[100:101], v[100:101], v[96:97]
	v_pk_mul_f32 v[98:99], v[100:101], s[72:73] op_sel_hi:[1,0]
	v_pk_add_f32 v[98:99], v[98:99], v[102:103] neg_lo:[0,1] neg_hi:[0,1]
	v_cvt_pk_bf16_f32 v240, v98, v99
	global_store_dword v105, v240, s[76:77] offset:1024
	v_lshlrev_b32_e32 v102, 16, v84
	v_and_b32_e32 v103, 0xffff0000, v84
	v_lshlrev_b32_e32 v96, 16, v82
	v_and_b32_e32 v97, 0xffff0000, v82
	v_pk_add_f32 v[96:97], v[102:103], v[96:97] neg_lo:[0,1] neg_hi:[0,1]
	v_pk_add_f32 v[100:101], v[100:101], v[96:97]
	v_pk_mul_f32 v[98:99], v[100:101], s[72:73] op_sel_hi:[1,0]
	v_pk_add_f32 v[98:99], v[98:99], v[102:103] neg_lo:[0,1] neg_hi:[0,1]
	v_cvt_pk_bf16_f32 v241, v98, v99
	global_store_dword v105, v241, s[76:77] offset:3072
	v_lshlrev_b32_e32 v102, 16, v85
	v_and_b32_e32 v103, 0xffff0000, v85
	v_lshlrev_b32_e32 v96, 16, v83
	v_and_b32_e32 v97, 0xffff0000, v83
	v_pk_add_f32 v[96:97], v[102:103], v[96:97] neg_lo:[0,1] neg_hi:[0,1]
	v_pk_add_f32 v[100:101], v[100:101], v[96:97]
	v_pk_mul_f32 v[98:99], v[100:101], s[72:73] op_sel_hi:[1,0]
	v_pk_add_f32 v[98:99], v[98:99], v[102:103] neg_lo:[0,1] neg_hi:[0,1]
	v_cvt_pk_bf16_f32 v104, v98, v99
	s_add_u32 s76, s76, 0x2000
	s_addc_u32 s77, s77, 0
	global_store_dword v105, v104, s[76:77] offset:-3072
	v_lshlrev_b32_e32 v102, 16, v86
	v_and_b32_e32 v103, 0xffff0000, v86
	v_lshlrev_b32_e32 v96, 16, v84
	v_and_b32_e32 v97, 0xffff0000, v84
	v_pk_add_f32 v[96:97], v[102:103], v[96:97] neg_lo:[0,1] neg_hi:[0,1]
	v_pk_add_f32 v[100:101], v[100:101], v[96:97]
	v_pk_mul_f32 v[98:99], v[100:101], s[72:73] op_sel_hi:[1,0]
	v_pk_add_f32 v[98:99], v[98:99], v[102:103] neg_lo:[0,1] neg_hi:[0,1]
	v_cvt_pk_bf16_f32 v239, v98, v99
	global_store_dword v105, v239, s[76:77] offset:-1024
	v_lshlrev_b32_e32 v102, 16, v87
	v_and_b32_e32 v103, 0xffff0000, v87
	v_lshlrev_b32_e32 v96, 16, v85
	v_and_b32_e32 v97, 0xffff0000, v85
	v_pk_add_f32 v[96:97], v[102:103], v[96:97] neg_lo:[0,1] neg_hi:[0,1]
	v_pk_add_f32 v[100:101], v[100:101], v[96:97]
	v_pk_mul_f32 v[98:99], v[100:101], s[72:73] op_sel_hi:[1,0]
	v_pk_add_f32 v[98:99], v[98:99], v[102:103] neg_lo:[0,1] neg_hi:[0,1]
	v_cvt_pk_bf16_f32 v240, v98, v99
	global_store_dword v105, v240, s[76:77] offset:1024
	v_lshlrev_b32_e32 v102, 16, v88
	v_and_b32_e32 v103, 0xffff0000, v88
	v_lshlrev_b32_e32 v96, 16, v86
	v_and_b32_e32 v97, 0xffff0000, v86
	v_pk_add_f32 v[96:97], v[102:103], v[96:97] neg_lo:[0,1] neg_hi:[0,1]
	v_pk_add_f32 v[100:101], v[100:101], v[96:97]
	v_pk_mul_f32 v[98:99], v[100:101], s[72:73] op_sel_hi:[1,0]
	v_pk_add_f32 v[98:99], v[98:99], v[102:103] neg_lo:[0,1] neg_hi:[0,1]
	v_cvt_pk_bf16_f32 v241, v98, v99
	global_store_dword v105, v241, s[76:77] offset:3072
	s_branch .Lmx_pool_done
.Lmx_ps0_0:
	s_mov_b32 s78, 0x3f800000
	s_mov_b32 s79, 0x3f800000
	v_mul_f32_e32 v98, s79, v100
	v_fma_f32 v96, -v98, s78, v100
	v_fma_f32 v98, v96, s79, v98
	v_mul_f32_e32 v99, s79, v101
	v_fma_f32 v96, -v99, s78, v101
	v_fma_f32 v99, v96, s79, v99
	s_branch .Lmx_pb0_0
.Lmx_pool1:
	v_lshlrev_b32_e32 v100, 16, v187
	v_and_b32_e32 v101, 0xffff0000, v187
	v_lshlrev_b32_e32 v96, 16, v186
	v_and_b32_e32 v97, 0xffff0000, v186
	v_pk_add_f32 v[100:101], v[100:101], v[96:97]
	v_lshlrev_b32_e32 v96, 16, v185
	v_and_b32_e32 v97, 0xffff0000, v185
	v_pk_add_f32 v[100:101], v[100:101], v[96:97]
	v_lshlrev_b32_e32 v96, 16, v184
	v_and_b32_e32 v97, 0xffff0000, v184
	v_pk_add_f32 v[100:101], v[100:101], v[96:97]
	v_lshlrev_b32_e32 v102, 16, v187
	v_and_b32_e32 v103, 0xffff0000, v187
	s_cmp_eq_u32 s64, 0
	s_cbranch_scc1 .Lmx_ps1_0
	v_pk_mul_f32 v[98:99], v[100:101], s[72:73] op_sel_hi:[1,0]
; __device__ __forceinline__ unsigned pk2(float lo, float hi) { f32x2v v = {lo, hi}; b16x2v b = __builtin_convertvector(v, b16x2v); return __builtin_bit_cast(unsigned, b); }
; __device__ __forceinline__ f32x2v bf2(unsigned v) { return (f32x2v){bflo(v), bfhi(v)}; }
; template <int W>
; __device__ __forceinline__ void pool_prompt_w(const unsigned (&pin)[31], int t0, unsigned* dst  ) {
;     f32x2v s = {0.f, 0.f};
; #pragma unroll
;     for (int i = 0; i < W; ++i) s = s + bf2(pin[15 - i]);
; #pragma unroll
;     for (int t = 0; t < 16; ++t) {
;         if (t > 0) s = s + (bf2(pin[15 + t]) - bf2(pin[15 + t - W]));
;         const float cnt = (float)min(t0 + t + 1, W); const f32x2v cur = bf2(pin[15 + t]);
;         dst[(size_t)t * 512] = pk2(s.x / cnt - cur.x, s.y / cnt - cur.y);
.Lmx_pb1_0:
	v_pk_add_f32 v[98:99], v[98:99], v[102:103] neg_lo:[0,1] neg_hi:[0,1]
	v_cvt_pk_bf16_f32 v104, v98, v99
	s_waitcnt vmcnt(47)
	global_store_dword v105, v104, s[76:77] offset:-3072
	v_lshlrev_b32_e32 v102, 16, v188
	v_and_b32_e32 v103, 0xffff0000, v188
	v_lshlrev_b32_e32 v96, 16, v184
	v_and_b32_e32 v97, 0xffff0000, v184
	v_pk_add_f32 v[96:97], v[102:103], v[96:97] neg_lo:[0,1] neg_hi:[0,1]
	v_pk_add_f32 v[100:101], v[100:101], v[96:97]
	s_cmp_eq_u32 s64, 0
	s_cbranch_scc1 .Lmx_ps1_1
	v_pk_mul_f32 v[98:99], v[100:101], s[72:73] op_sel_hi:[1,0]
.Lmx_pb1_1:
	v_pk_add_f32 v[98:99], v[98:99], v[102:103] neg_lo:[0,1] neg_hi:[0,1]
	v_cvt_pk_bf16_f32 v239, v98, v99
	global_store_dword v105, v239, s[76:77] offset:-1024
	v_lshlrev_b32_e32 v102, 16, v189
	v_and_b32_e32 v103, 0xffff0000, v189
	v_lshlrev_b32_e32 v96, 16, v185
	v_and_b32_e32 v97, 0xffff0000, v185
	v_pk_add_f32 v[96:97], v[102:103], v[96:97] neg_lo:[0,1] neg_hi:[0,1]
	v_pk_add_f32 v[100:101], v[100:101], v[96:97]
	s_cmp_eq_u32 s64, 0
	s_cbranch_scc1 .Lmx_ps1_2
	v_pk_mul_f32 v[98:99], v[100:101], s[72:73] op_sel_hi:[1,0]
; __device__ __forceinline__ unsigned pk2(float lo, float hi) { f32x2v v = {lo, hi}; b16x2v b = __builtin_convertvector(v, b16x2v); return __builtin_bit_cast(unsigned, b); }
; __device__ __forceinline__ f32x2v bf2(unsigned v) { return (f32x2v){bflo(v), bfhi(v)}; }
; template <int W>
; __device__ __forceinline__ void pool_prompt_w(const unsigned (&pin)[31], int t0, unsigned* dst  ) {
;     f32x2v s = {0.f, 0.f};
; #pragma unroll
;     for (int i = 0; i < W; ++i) s = s + bf2(pin[15 - i]);
; #pragma unroll
;     for (int t = 0; t < 16; ++t) {
;         if (t > 0) s = s + (bf2(pin[15 + t]) - bf2(pin[15 + t - W]));
;         const float cnt = (float)min(t0 + t + 1, W); const f32x2v cur = bf2(pin[15 + t]);
;         dst[(size_t)t * 512] = pk2(s.x / cnt - cur.x, s.y / cnt - cur.y);
.Lmx_pb1_2:
	v_pk_add_f32 v[98:99], v[98:99], v[102:103] neg_lo:[0,1] neg_hi:[0,1]
	v_cvt_pk_bf16_f32 v240, v98, v99
	global_store_dword v105, v240, s[76:77] offset:1024
	v_lshlrev_b32_e32 v102, 16, v190
	v_and_b32_e32 v103, 0xffff0000, v190
	v_lshlrev_b32_e32 v96, 16, v186
	v_and_b32_e32 v97, 0xffff0000, v186
	v_pk_add_f32 v[96:97], v[102:103], v[96:97] neg_lo:[0,1] neg_hi:[0,1]
	v_pk_add_f32 v[100:101], v[100:101], v[96:97]
	v_pk_mul_f32 v[98:99], v[100:101], s[72:73] op_sel_hi:[1,0]
	v_pk_add_f32 v[98:99], v[98:99], v[102:103] neg_lo:[0,1] neg_hi:[0,1]
	v_cvt_pk_bf16_f32 v241, v98, v99
	global_store_dword v105, v241, s[76:77] offset:3072
	v_lshlrev_b32_e32 v102, 16, v191
	v_and_b32_e32 v103, 0xffff0000, v191
	v_lshlrev_b32_e32 v96, 16, v187
	v_and_b32_e32 v97, 0xffff0000, v187
	v_pk_add_f32 v[96:97], v[102:103], v[96:97] neg_lo:[0,1] neg_hi:[0,1]
	v_pk_add_f32 v[100:101], v[100:101], v[96:97]
	v_pk_mul_f32 v[98:99], v[100:101], s[72:73] op_sel_hi:[1,0]
	v_pk_add_f32 v[98:99], v[98:99], v[102:103] neg_lo:[0,1] neg_hi:[0,1]
	v_cvt_pk_bf16_f32 v104, v98, v99
	s_add_u32 s76, s76, 0x2000
	s_addc_u32 s77, s77, 0
	global_store_dword v105, v104, s[76:77] offset:-3072
	v_lshlrev_b32_e32 v102, 16, v78
	v_and_b32_e32 v103, 0xffff0000, v78
	v_lshlrev_b32_e32 v96, 16, v188
	v_and_b32_e32 v97, 0xffff0000, v188
	v_pk_add_f32 v[96:97], v[102:103], v[96:97] neg_lo:[0,1] neg_hi:[0,1]
	v_pk_add_f32 v[100:101], v[100:101], v[96:97]
	v_pk_mul_f32 v[98:99], v[100:101], s[72:73] op_sel_hi:[1,0]
	v_pk_add_f32 v[98:99], v[98:99], v[102:103] neg_lo:[0,1] neg_hi:[0,1]
	v_cvt_pk_bf16_f32 v239, v98, v99
	global_store_dword v105, v239, s[76:77] offset:-1024
	v_lshlrev_b32_e32 v102, 16, v79
	v_and_b32_e32 v103, 0xffff0000, v79
	v_lshlrev_b32_e32 v96, 16, v189
	v_and_b32_e32 v97, 0xffff0000, v189
	v_pk_add_f32 v[96:97], v[102:103], v[96:97] neg_lo:[0,1] neg_hi:[0,1]
	v_pk_add_f32 v[100:101], v[100:101], v[96:97]
	v_pk_mul_f32 v[98:99], v[100:101], s[72:73] op_sel_hi:[1,0]
	v_pk_add_f32 v[98:99], v[98:99], v[102:103] neg_lo:[0,1] neg_hi:[0,1]
	v_cvt_pk_bf16_f32 v240, v98, v99
	global_store_dword v105, v240, s[76:77] offset:1024
	v_lshlrev_b32_e32 v102, 16, v80
	v_and_b32_e32 v103, 0xffff0000, v80
	v_lshlrev_b32_e32 v96, 16, v190
	v_and_b32_e32 v97, 0xffff0000, v190
	v_pk_add_f32 v[96:97], v[102:103], v[96:97] neg_lo:[0,1] neg_hi:[0,1]
	v_pk_add_f32 v[100:101], v[100:101], v[96:97]
	v_pk_mul_f32 v[98:99], v[100:101], s[72:73] op_sel_hi:[1,0]
	v_pk_add_f32 v[98:99], v[98:99], v[102:103] neg_lo:[0,1] neg_hi:[0,1]
	v_cvt_pk_bf16_f32 v241, v98, v99
	global_store_dword v105, v241, s[76:77] offset:3072
	v_lshlrev_b32_e32 v102, 16, v81
	v_and_b32_e32 v103, 0xffff0000, v81
	v_lshlrev_b32_e32 v96, 16, v191
	v_and_b32_e32 v97, 0xffff0000, v191
	v_pk_add_f32 v[96:97], v[102:103], v[96:97] neg_lo:[0,1] neg_hi:[0,1]
	v_pk_add_f32 v[100:101], v[100:101], v[96:97]
	v_pk_mul_f32 v[98:99], v[100:101], s[72:73] op_sel_hi:[1,0]
	v_pk_add_f32 v[98:99], v[98:99], v[102:103] neg_lo:[0,1] neg_hi:[0,1]
	v_cvt_pk_bf16_f32 v104, v98, v99
	s_add_u32 s76, s76, 0x2000
	s_addc_u32 s77, s77, 0
	global_store_dword v105, v104, s[76:77] offset:-3072
	v_lshlrev_b32_e32 v102, 16, v82
	v_and_b32_e32 v103, 0xffff0000, v82
	v_lshlrev_b32_e32 v96, 16, v78
	v_and_b32_e32 v97, 0xffff0000, v78
	v_pk_add_f32 v[96:97], v[102:103], v[96:97] neg_lo:[0,1] neg_hi:[0,1]
	v_pk_add_f32 v[100:101], v[100:101], v[96:97]
	v_pk_mul_f32 v[98:99], v[100:101], s[72:73] op_sel_hi:[1,0]
	v_pk_add_f32 v[98:99], v[98:99], v[102:103] neg_lo:[0,1] neg_hi:[0,1]
	v_cvt_pk_bf16_f32 v239, v98, v99
	global_store_dword v105, v239, s[76:77] offset:-1024
	v_lshlrev_b32_e32 v102, 16, v83
	v_and_b32_e32 v103, 0xffff0000, v83
	v_lshlrev_b32_e32 v96, 16, v79
	v_and_b32_e32 v97, 0xffff0000, v79
	v_pk_add_f32 v[96:97], v[102:103], v[96:97] neg_lo:[0,1] neg_hi:[0,1]
	v_pk_add_f32 v[100:101], v[100:101], v[96:97]
	v_pk_mul_f32 v[98:99], v[100:101], s[72:73] op_sel_hi:[1,0]
	v_pk_add_f32 v[98:99], v[98:99], v[102:103] neg_lo:[0,1] neg_hi:[0,1]
	v_cvt_pk_bf16_f32 v240, v98, v99
	global_store_dword v105, v240, s[76:77] offset:1024
	v_lshlrev_b32_e32 v102, 16, v84
	v_and_b32_e32 v103, 0xffff0000, v84
	v_lshlrev_b32_e32 v96, 16, v80
	v_and_b32_e32 v97, 0xffff0000, v80
	v_pk_add_f32 v[96:97], v[102:103], v[96:97] neg_lo:[0,1] neg_hi:[0,1]
	v_pk_add_f32 v[100:101], v[100:101], v[96:97]
	v_pk_mul_f32 v[98:99], v[100:101], s[72:73] op_sel_hi:[1,0]
	v_pk_add_f32 v[98:99], v[98:99], v[102:103] neg_lo:[0,1] neg_hi:[0,1]
	v_cvt_pk_bf16_f32 v241, v98, v99
	global_store_dword v105, v241, s[76:77] offset:3072
	v_lshlrev_b32_e32 v102, 16, v85
	v_and_b32_e32 v103, 0xffff0000, v85
	v_lshlrev_b32_e32 v96, 16, v81
	v_and_b32_e32 v97, 0xffff0000, v81
	v_pk_add_f32 v[96:97], v[102:103], v[96:97] neg_lo:[0,1] neg_hi:[0,1]
	v_pk_add_f32 v[100:101], v[100:101], v[96:97]
	v_pk_mul_f32 v[98:99], v[100:101], s[72:73] op_sel_hi:[1,0]
	v_pk_add_f32 v[98:99], v[98:99], v[102:103] neg_lo:[0,1] neg_hi:[0,1]
	v_cvt_pk_bf16_f32 v104, v98, v99
	s_add_u32 s76, s76, 0x2000
	s_addc_u32 s77, s77, 0
	global_store_dword v105, v104, s[76:77] offset:-3072
	v_lshlrev_b32_e32 v102, 16, v86
	v_and_b32_e32 v103, 0xffff0000, v86
	v_lshlrev_b32_e32 v96, 16, v82
	v_and_b32_e32 v97, 0xffff0000, v82
	v_pk_add_f32 v[96:97], v[102:103], v[96:97] neg_lo:[0,1] neg_hi:[0,1]
	v_pk_add_f32 v[100:101], v[100:101], v[96:97]
	v_pk_mul_f32 v[98:99], v[100:101], s[72:73] op_sel_hi:[1,0]
	v_pk_add_f32 v[98:99], v[98:99], v[102:103] neg_lo:[0,1] neg_hi:[0,1]
	v_cvt_pk_bf16_f32 v239, v98, v99
	global_store_dword v105, v239, s[76:77] offset:-1024
	v_lshlrev_b32_e32 v102, 16, v87
	v_and_b32_e32 v103, 0xffff0000, v87
	v_lshlrev_b32_e32 v96, 16, v83
	v_and_b32_e32 v97, 0xffff0000, v83
	v_pk_add_f32 v[96:97], v[102:103], v[96:97] neg_lo:[0,1] neg_hi:[0,1]
	v_pk_add_f32 v[100:101], v[100:101], v[96:97]
	v_pk_mul_f32 v[98:99], v[100:101], s[72:73] op_sel_hi:[1,0]
	v_pk_add_f32 v[98:99], v[98:99], v[102:103] neg_lo:[0,1] neg_hi:[0,1]
	v_cvt_pk_bf16_f32 v240, v98, v99
	global_store_dword v105, v240, s[76:77] offset:1024
	v_lshlrev_b32_e32 v102, 16, v88
	v_and_b32_e32 v103, 0xffff0000, v88
	v_lshlrev_b32_e32 v96, 16, v84
	v_and_b32_e32 v97, 0xffff0000, v84
	v_pk_add_f32 v[96:97], v[102:103], v[96:97] neg_lo:[0,1] neg_hi:[0,1]
	v_pk_add_f32 v[100:101], v[100:101], v[96:97]
	v_pk_mul_f32 v[98:99], v[100:101], s[72:73] op_sel_hi:[1,0]
	v_pk_add_f32 v[98:99], v[98:99], v[102:103] neg_lo:[0,1] neg_hi:[0,1]
	v_cvt_pk_bf16_f32 v241, v98, v99
	global_store_dword v105, v241, s[76:77] offset:3072
	s_branch .Lmx_pool_done

; __device__ __forceinline__ unsigned pk2(float lo, float hi) { f32x2v v = {lo, hi}; b16x2v b = __builtin_convertvector(v, b16x2v); return __builtin_bit_cast(unsigned, b); }
; __device__ __forceinline__ f32x2v bf2(unsigned v) { return (f32x2v){bflo(v), bfhi(v)}; }
; template <int W>
; __device__ __forceinline__ void pool_prompt_w(const unsigned (&pin)[31], int t0, unsigned* dst  ) {
;     f32x2v s = {0.f, 0.f};
; #pragma unroll
;     for (int i = 0; i < W; ++i) s = s + bf2(pin[15 - i]);
; #pragma unroll
;     for (int t = 0; t < 16; ++t) {
;         if (t > 0) s = s + (bf2(pin[15 + t]) - bf2(pin[15 + t - W]));
;         const float cnt = (float)min(t0 + t + 1, W); const f32x2v cur = bf2(pin[15 + t]);
;         dst[(size_t)t * 512] = pk2(s.x / cnt - cur.x, s.y / cnt - cur.y);
.Lmx_ps1_1:
	s_mov_b32 s78, 0x40000000
	s_mov_b32 s79, 0x3f000000
	v_mul_f32_e32 v98, s79, v100
	v_fma_f32 v96, -v98, s78, v100
	v_fma_f32 v98, v96, s79, v98
	v_mul_f32_e32 v99, s79, v101
	v_fma_f32 v96, -v99, s78, v101
	v_fma_f32 v99, v96, s79, v99
	s_branch .Lmx_pb1_1
.Lmx_ps1_2:
	s_mov_b32 s78, 0x40400000
	s_mov_b32 s79, 0x3eaaaaab
	v_mul_f32_e32 v98, s79, v100
	v_fma_f32 v96, -v98, s78, v100
	v_fma_f32 v98, v96, s79, v98
	v_mul_f32_e32 v99, s79, v101
	v_fma_f32 v96, -v99, s78, v101
	v_fma_f32 v99, v96, s79, v99
	s_branch .Lmx_pb1_2
.Lmx_pool2:
	v_lshlrev_b32_e32 v100, 16, v187
	v_and_b32_e32 v101, 0xffff0000, v187
	v_lshlrev_b32_e32 v96, 16, v186
	v_and_b32_e32 v97, 0xffff0000, v186
	v_pk_add_f32 v[100:101], v[100:101], v[96:97]
	v_lshlrev_b32_e32 v96, 16, v185
	v_and_b32_e32 v97, 0xffff0000, v185
	v_pk_add_f32 v[100:101], v[100:101], v[96:97]
	v_lshlrev_b32_e32 v96, 16, v184
	v_and_b32_e32 v97, 0xffff0000, v184
	v_pk_add_f32 v[100:101], v[100:101], v[96:97]
	v_lshlrev_b32_e32 v96, 16, v183
	v_and_b32_e32 v97, 0xffff0000, v183
	v_pk_add_f32 v[100:101], v[100:101], v[96:97]
	v_lshlrev_b32_e32 v96, 16, v182
	v_and_b32_e32 v97, 0xffff0000, v182
	v_pk_add_f32 v[100:101], v[100:101], v[96:97]
	v_lshlrev_b32_e32 v96, 16, v181
	v_and_b32_e32 v97, 0xffff0000, v181
	v_pk_add_f32 v[100:101], v[100:101], v[96:97]
	v_lshlrev_b32_e32 v96, 16, v180
	v_and_b32_e32 v97, 0xffff0000, v180
	v_pk_add_f32 v[100:101], v[100:101], v[96:97]
	v_lshlrev_b32_e32 v102, 16, v187
	v_and_b32_e32 v103, 0xffff0000, v187
	s_cmp_eq_u32 s64, 0
	s_cbranch_scc1 .Lmx_ps2_0
	v_pk_mul_f32 v[98:99], v[100:101], s[72:73] op_sel_hi:[1,0]
.Lmx_pb2_0:
	v_pk_add_f32 v[98:99], v[98:99], v[102:103] neg_lo:[0,1] neg_hi:[0,1]
	v_cvt_pk_bf16_f32 v104, v98, v99
	s_waitcnt vmcnt(47)
	global_store_dword v105, v104, s[76:77] offset:-3072
	v_lshlrev_b32_e32 v102, 16, v188
	v_and_b32_e32 v103, 0xffff0000, v188
	v_lshlrev_b32_e32 v96, 16, v180
	v_and_b32_e32 v97, 0xffff0000, v180
	v_pk_add_f32 v[96:97], v[102:103], v[96:97] neg_lo:[0,1] neg_hi:[0,1]
	v_pk_add_f32 v[100:101], v[100:101], v[96:97]
	s_cmp_eq_u32 s64, 0
	s_cbranch_scc1 .Lmx_ps2_1
	v_pk_mul_f32 v[98:99], v[100:101], s[72:73] op_sel_hi:[1,0]
.Lmx_pb2_1:
	v_pk_add_f32 v[98:99], v[98:99], v[102:103] neg_lo:[0,1] neg_hi:[0,1]
	v_cvt_pk_bf16_f32 v239, v98, v99
	global_store_dword v105, v239, s[76:77] offset:-1024
	v_lshlrev_b32_e32 v102, 16, v189
	v_and_b32_e32 v103, 0xffff0000, v189
	v_lshlrev_b32_e32 v96, 16, v181
	v_and_b32_e32 v97, 0xffff0000, v181
	v_pk_add_f32 v[96:97], v[102:103], v[96:97] neg_lo:[0,1] neg_hi:[0,1]
	v_pk_add_f32 v[100:101], v[100:101], v[96:97]
	s_cmp_eq_u32 s64, 0
	s_cbranch_scc1 .Lmx_ps2_2
	v_pk_mul_f32 v[98:99], v[100:101], s[72:73] op_sel_hi:[1,0]
.Lmx_pb2_2:
	v_pk_add_f32 v[98:99], v[98:99], v[102:103] neg_lo:[0,1] neg_hi:[0,1]
	v_cvt_pk_bf16_f32 v240, v98, v99
	global_store_dword v105, v240, s[76:77] offset:1024
	v_lshlrev_b32_e32 v102, 16, v190
	v_and_b32_e32 v103, 0xffff0000, v190
	v_lshlrev_b32_e32 v96, 16, v182
	v_and_b32_e32 v97, 0xffff0000, v182
	v_pk_add_f32 v[96:97], v[102:103], v[96:97] neg_lo:[0,1] neg_hi:[0,1]
	v_pk_add_f32 v[100:101], v[100:101], v[96:97]
	s_cmp_eq_u32 s64, 0
	s_cbranch_scc1 .Lmx_ps2_3
	v_pk_mul_f32 v[98:99], v[100:101], s[72:73] op_sel_hi:[1,0]
.Lmx_pb2_3:
	v_pk_add_f32 v[98:99], v[98:99], v[102:103] neg_lo:[0,1] neg_hi:[0,1]
	v_cvt_pk_bf16_f32 v241, v98, v99
	global_store_dword v105, v241, s[76:77] offset:3072
	v_lshlrev_b32_e32 v102, 16, v191
	v_and_b32_e32 v103, 0xffff0000, v191
	v_lshlrev_b32_e32 v96, 16, v183
	v_and_b32_e32 v97, 0xffff0000, v183
	v_pk_add_f32 v[96:97], v[102:103], v[96:97] neg_lo:[0,1] neg_hi:[0,1]
	v_pk_add_f32 v[100:101], v[100:101], v[96:97]
	s_cmp_eq_u32 s64, 0
	s_cbranch_scc1 .Lmx_ps2_4
	v_pk_mul_f32 v[98:99], v[100:101], s[72:73] op_sel_hi:[1,0]
.Lmx_pb2_4:
	v_pk_add_f32 v[98:99], v[98:99], v[102:103] neg_lo:[0,1] neg_hi:[0,1]
	v_cvt_pk_bf16_f32 v104, v98, v99
	s_add_u32 s76, s76, 0x2000
	s_addc_u32 s77, s77, 0
	global_store_dword v105, v104, s[76:77] offset:-3072
	v_lshlrev_b32_e32 v102, 16, v78
	v_and_b32_e32 v103, 0xffff0000, v78
	v_lshlrev_b32_e32 v96, 16, v184
	v_and_b32_e32 v97, 0xffff0000, v184
	v_pk_add_f32 v[96:97], v[102:103], v[96:97] neg_lo:[0,1] neg_hi:[0,1]
	v_pk_add_f32 v[100:101], v[100:101], v[96:97]
	s_cmp_eq_u32 s64, 0
	s_cbranch_scc1 .Lmx_ps2_5
	v_pk_mul_f32 v[98:99], v[100:101], s[72:73] op_sel_hi:[1,0]
.Lmx_pb2_5:
	v_pk_add_f32 v[98:99], v[98:99], v[102:103] neg_lo:[0,1] neg_hi:[0,1]
	v_cvt_pk_bf16_f32 v239, v98, v99
	global_store_dword v105, v239, s[76:77] offset:-1024
	v_lshlrev_b32_e32 v102, 16, v79
	v_and_b32_e32 v103, 0xffff0000, v79
	v_lshlrev_b32_e32 v96, 16, v185
	v_and_b32_e32 v97, 0xffff0000, v185
	v_pk_add_f32 v[96:97], v[102:103], v[96:97] neg_lo:[0,1] neg_hi:[0,1]
	v_pk_add_f32 v[100:101], v[100:101], v[96:97]
	s_cmp_eq_u32 s64, 0
	s_cbranch_scc1 .Lmx_ps2_6
	v_pk_mul_f32 v[98:99], v[100:101], s[72:73] op_sel_hi:[1,0]
; __device__ __forceinline__ unsigned pk2(float lo, float hi) { f32x2v v = {lo, hi}; b16x2v b = __builtin_convertvector(v, b16x2v); return __builtin_bit_cast(unsigned, b); }
; __device__ __forceinline__ f32x2v bf2(unsigned v) { return (f32x2v){bflo(v), bfhi(v)}; }
; template <int W>
; __device__ __forceinline__ void pool_prompt_w(const unsigned (&pin)[31], int t0, unsigned* dst  ) {
;     f32x2v s = {0.f, 0.f};
; #pragma unroll
;     for (int i = 0; i < W; ++i) s = s + bf2(pin[15 - i]);
; #pragma unroll
;     for (int t = 0; t < 16; ++t) {
;         if (t > 0) s = s + (bf2(pin[15 + t]) - bf2(pin[15 + t - W]));
;         const float cnt = (float)min(t0 + t + 1, W); const f32x2v cur = bf2(pin[15 + t]);
;         dst[(size_t)t * 512] = pk2(s.x / cnt - cur.x, s.y / cnt - cur.y);
.Lmx_pb2_6:
	v_pk_add_f32 v[98:99], v[98:99], v[102:103] neg_lo:[0,1] neg_hi:[0,1]
	v_cvt_pk_bf16_f32 v240, v98, v99
	global_store_dword v105, v240, s[76:77] offset:1024
	v_lshlrev_b32_e32 v102, 16, v80
	v_and_b32_e32 v103, 0xffff0000, v80
	v_lshlrev_b32_e32 v96, 16, v186
	v_and_b32_e32 v97, 0xffff0000, v186
	v_pk_add_f32 v[96:97], v[102:103], v[96:97] neg_lo:[0,1] neg_hi:[0,1]
	v_pk_add_f32 v[100:101], v[100:101], v[96:97]
	v_pk_mul_f32 v[98:99], v[100:101], s[72:73] op_sel_hi:[1,0]
	v_pk_add_f32 v[98:99], v[98:99], v[102:103] neg_lo:[0,1] neg_hi:[0,1]
	v_cvt_pk_bf16_f32 v241, v98, v99
	global_store_dword v105, v241, s[76:77] offset:3072
	v_lshlrev_b32_e32 v102, 16, v81
	v_and_b32_e32 v103, 0xffff0000, v81
	v_lshlrev_b32_e32 v96, 16, v187
	v_and_b32_e32 v97, 0xffff0000, v187
	v_pk_add_f32 v[96:97], v[102:103], v[96:97] neg_lo:[0,1] neg_hi:[0,1]
	v_pk_add_f32 v[100:101], v[100:101], v[96:97]
	v_pk_mul_f32 v[98:99], v[100:101], s[72:73] op_sel_hi:[1,0]
	v_pk_add_f32 v[98:99], v[98:99], v[102:103] neg_lo:[0,1] neg_hi:[0,1]
	v_cvt_pk_bf16_f32 v104, v98, v99
	s_add_u32 s76, s76, 0x2000
	s_addc_u32 s77, s77, 0
	global_store_dword v105, v104, s[76:77] offset:-3072
	v_lshlrev_b32_e32 v102, 16, v82
	v_and_b32_e32 v103, 0xffff0000, v82
	v_lshlrev_b32_e32 v96, 16, v188
	v_and_b32_e32 v97, 0xffff0000, v188
	v_pk_add_f32 v[96:97], v[102:103], v[96:97] neg_lo:[0,1] neg_hi:[0,1]
	v_pk_add_f32 v[100:101], v[100:101], v[96:97]
	v_pk_mul_f32 v[98:99], v[100:101], s[72:73] op_sel_hi:[1,0]
	v_pk_add_f32 v[98:99], v[98:99], v[102:103] neg_lo:[0,1] neg_hi:[0,1]
	v_cvt_pk_bf16_f32 v239, v98, v99
	global_store_dword v105, v239, s[76:77] offset:-1024
	v_lshlrev_b32_e32 v102, 16, v83
	v_and_b32_e32 v103, 0xffff0000, v83
	v_lshlrev_b32_e32 v96, 16, v189
	v_and_b32_e32 v97, 0xffff0000, v189
	v_pk_add_f32 v[96:97], v[102:103], v[96:97] neg_lo:[0,1] neg_hi:[0,1]
	v_pk_add_f32 v[100:101], v[100:101], v[96:97]
	v_pk_mul_f32 v[98:99], v[100:101], s[72:73] op_sel_hi:[1,0]
	v_pk_add_f32 v[98:99], v[98:99], v[102:103] neg_lo:[0,1] neg_hi:[0,1]
	v_cvt_pk_bf16_f32 v240, v98, v99
	global_store_dword v105, v240, s[76:77] offset:1024
	v_lshlrev_b32_e32 v102, 16, v84
	v_and_b32_e32 v103, 0xffff0000, v84
	v_lshlrev_b32_e32 v96, 16, v190
	v_and_b32_e32 v97, 0xffff0000, v190
	v_pk_add_f32 v[96:97], v[102:103], v[96:97] neg_lo:[0,1] neg_hi:[0,1]
	v_pk_add_f32 v[100:101], v[100:101], v[96:97]
	v_pk_mul_f32 v[98:99], v[100:101], s[72:73] op_sel_hi:[1,0]
	v_pk_add_f32 v[98:99], v[98:99], v[102:103] neg_lo:[0,1] neg_hi:[0,1]
	v_cvt_pk_bf16_f32 v241, v98, v99
	global_store_dword v105, v241, s[76:77] offset:3072
	v_lshlrev_b32_e32 v102, 16, v85
	v_and_b32_e32 v103, 0xffff0000, v85
	v_lshlrev_b32_e32 v96, 16, v191
	v_and_b32_e32 v97, 0xffff0000, v191
	v_pk_add_f32 v[96:97], v[102:103], v[96:97] neg_lo:[0,1] neg_hi:[0,1]
	v_pk_add_f32 v[100:101], v[100:101], v[96:97]
	v_pk_mul_f32 v[98:99], v[100:101], s[72:73] op_sel_hi:[1,0]
	v_pk_add_f32 v[98:99], v[98:99], v[102:103] neg_lo:[0,1] neg_hi:[0,1]
	v_cvt_pk_bf16_f32 v104, v98, v99
	s_add_u32 s76, s76, 0x2000
	s_addc_u32 s77, s77, 0
	global_store_dword v105, v104, s[76:77] offset:-3072
	v_lshlrev_b32_e32 v102, 16, v86
	v_and_b32_e32 v103, 0xffff0000, v86
	v_lshlrev_b32_e32 v96, 16, v78
	v_and_b32_e32 v97, 0xffff0000, v78
	v_pk_add_f32 v[96:97], v[102:103], v[96:97] neg_lo:[0,1] neg_hi:[0,1]
	v_pk_add_f32 v[100:101], v[100:101], v[96:97]
	v_pk_mul_f32 v[98:99], v[100:101], s[72:73] op_sel_hi:[1,0]
	v_pk_add_f32 v[98:99], v[98:99], v[102:103] neg_lo:[0,1] neg_hi:[0,1]
	v_cvt_pk_bf16_f32 v239, v98, v99
	global_store_dword v105, v239, s[76:77] offset:-1024
	v_lshlrev_b32_e32 v102, 16, v87
	v_and_b32_e32 v103, 0xffff0000, v87
	v_lshlrev_b32_e32 v96, 16, v79
	v_and_b32_e32 v97, 0xffff0000, v79
	v_pk_add_f32 v[96:97], v[102:103], v[96:97] neg_lo:[0,1] neg_hi:[0,1]
	v_pk_add_f32 v[100:101], v[100:101], v[96:97]
	v_pk_mul_f32 v[98:99], v[100:101], s[72:73] op_sel_hi:[1,0]
	v_pk_add_f32 v[98:99], v[98:99], v[102:103] neg_lo:[0,1] neg_hi:[0,1]
	v_cvt_pk_bf16_f32 v240, v98, v99
	global_store_dword v105, v240, s[76:77] offset:1024
	v_lshlrev_b32_e32 v102, 16, v88
	v_and_b32_e32 v103, 0xffff0000, v88
	v_lshlrev_b32_e32 v96, 16, v80
	v_and_b32_e32 v97, 0xffff0000, v80
	v_pk_add_f32 v[96:97], v[102:103], v[96:97] neg_lo:[0,1] neg_hi:[0,1]
	v_pk_add_f32 v[100:101], v[100:101], v[96:97]
	v_pk_mul_f32 v[98:99], v[100:101], s[72:73] op_sel_hi:[1,0]
	v_pk_add_f32 v[98:99], v[98:99], v[102:103] neg_lo:[0,1] neg_hi:[0,1]
	v_cvt_pk_bf16_f32 v241, v98, v99
	global_store_dword v105, v241, s[76:77] offset:3072
	s_branch .Lmx_pool_done

; __device__ __forceinline__ unsigned pk2(float lo, float hi) { f32x2v v = {lo, hi}; b16x2v b = __builtin_convertvector(v, b16x2v); return __builtin_bit_cast(unsigned, b); }
; __device__ __forceinline__ f32x2v bf2(unsigned v) { return (f32x2v){bflo(v), bfhi(v)}; }
; template <int W>
; __device__ __forceinline__ void pool_prompt_w(const unsigned (&pin)[31], int t0, unsigned* dst  ) {
;     f32x2v s = {0.f, 0.f};
; #pragma unroll
;     for (int i = 0; i < W; ++i) s = s + bf2(pin[15 - i]);
; #pragma unroll
;     for (int t = 0; t < 16; ++t) {
;         if (t > 0) s = s + (bf2(pin[15 + t]) - bf2(pin[15 + t - W]));
;         const float cnt = (float)min(t0 + t + 1, W); const f32x2v cur = bf2(pin[15 + t]);
;         dst[(size_t)t * 512] = pk2(s.x / cnt - cur.x, s.y / cnt - cur.y);
.Lmx_ps2_3:
	s_mov_b32 s78, 0x40800000
	s_mov_b32 s79, 0x3e800000
	v_mul_f32_e32 v98, s79, v100
	v_fma_f32 v96, -v98, s78, v100
	v_fma_f32 v98, v96, s79, v98
	v_mul_f32_e32 v99, s79, v101
	v_fma_f32 v96, -v99, s78, v101
	v_fma_f32 v99, v96, s79, v99
	s_branch .Lmx_pb2_3
.Lmx_ps2_4:
	s_mov_b32 s78, 0x40a00000
	s_mov_b32 s79, 0x3e4ccccd
	v_mul_f32_e32 v98, s79, v100
	v_fma_f32 v96, -v98, s78, v100
	v_fma_f32 v98, v96, s79, v98
	v_mul_f32_e32 v99, s79, v101
	v_fma_f32 v96, -v99, s78, v101
	v_fma_f32 v99, v96, s79, v99
	s_branch .Lmx_pb2_4
.Lmx_ps2_5:
	s_mov_b32 s78, 0x40c00000
	s_mov_b32 s79, 0x3e2aaaab
	v_mul_f32_e32 v98, s79, v100
	v_fma_f32 v96, -v98, s78, v100
	v_fma_f32 v98, v96, s79, v98
	v_mul_f32_e32 v99, s79, v101
	v_fma_f32 v96, -v99, s78, v101
	v_fma_f32 v99, v96, s79, v99
	s_branch .Lmx_pb2_5
.Lmx_ps2_6:
	s_mov_b32 s78, 0x40e00000
	s_mov_b32 s79, 0x3e124925
	v_mul_f32_e32 v98, s79, v100
	v_fma_f32 v96, -v98, s78, v100
	v_fma_f32 v98, v96, s79, v98
	v_mul_f32_e32 v99, s79, v101
	v_fma_f32 v96, -v99, s78, v101
	v_fma_f32 v99, v96, s79, v99
	s_branch .Lmx_pb2_6
.Lmx_pool3:
	v_lshlrev_b32_e32 v100, 16, v187
	v_and_b32_e32 v101, 0xffff0000, v187
	v_lshlrev_b32_e32 v96, 16, v186
	v_and_b32_e32 v97, 0xffff0000, v186
	v_pk_add_f32 v[100:101], v[100:101], v[96:97]
	v_lshlrev_b32_e32 v96, 16, v185
	v_and_b32_e32 v97, 0xffff0000, v185
	v_pk_add_f32 v[100:101], v[100:101], v[96:97]
	v_lshlrev_b32_e32 v96, 16, v184
	v_and_b32_e32 v97, 0xffff0000, v184
	v_pk_add_f32 v[100:101], v[100:101], v[96:97]
	v_lshlrev_b32_e32 v96, 16, v183
	v_and_b32_e32 v97, 0xffff0000, v183
	v_pk_add_f32 v[100:101], v[100:101], v[96:97]
	v_lshlrev_b32_e32 v96, 16, v182
	v_and_b32_e32 v97, 0xffff0000, v182
	v_pk_add_f32 v[100:101], v[100:101], v[96:97]
	v_lshlrev_b32_e32 v96, 16, v181
	v_and_b32_e32 v97, 0xffff0000, v181
	v_pk_add_f32 v[100:101], v[100:101], v[96:97]
	v_lshlrev_b32_e32 v96, 16, v180
	v_and_b32_e32 v97, 0xffff0000, v180
	v_pk_add_f32 v[100:101], v[100:101], v[96:97]
	v_lshlrev_b32_e32 v96, 16, v179
	v_and_b32_e32 v97, 0xffff0000, v179
	v_pk_add_f32 v[100:101], v[100:101], v[96:97]
	v_lshlrev_b32_e32 v96, 16, v178
	v_and_b32_e32 v97, 0xffff0000, v178
	v_pk_add_f32 v[100:101], v[100:101], v[96:97]
	v_lshlrev_b32_e32 v96, 16, v177
	v_and_b32_e32 v97, 0xffff0000, v177
	v_pk_add_f32 v[100:101], v[100:101], v[96:97]
	v_lshlrev_b32_e32 v96, 16, v176
	v_and_b32_e32 v97, 0xffff0000, v176
	v_pk_add_f32 v[100:101], v[100:101], v[96:97]
	v_lshlrev_b32_e32 v96, 16, v175
	v_and_b32_e32 v97, 0xffff0000, v175
	v_pk_add_f32 v[100:101], v[100:101], v[96:97]
	v_lshlrev_b32_e32 v96, 16, v174
	v_and_b32_e32 v97, 0xffff0000, v174
	v_pk_add_f32 v[100:101], v[100:101], v[96:97]
	v_lshlrev_b32_e32 v96, 16, v173
	v_and_b32_e32 v97, 0xffff0000, v173
	v_pk_add_f32 v[100:101], v[100:101], v[96:97]
	v_lshlrev_b32_e32 v96, 16, v172
	v_and_b32_e32 v97, 0xffff0000, v172
	v_pk_add_f32 v[100:101], v[100:101], v[96:97]
	v_lshlrev_b32_e32 v102, 16, v187
	v_and_b32_e32 v103, 0xffff0000, v187
	s_cmp_eq_u32 s64, 0
	s_cbranch_scc1 .Lmx_ps3_0
	v_pk_mul_f32 v[98:99], v[100:101], s[72:73] op_sel_hi:[1,0]
.Lmx_pb3_0:
	v_pk_add_f32 v[98:99], v[98:99], v[102:103] neg_lo:[0,1] neg_hi:[0,1]
	v_cvt_pk_bf16_f32 v104, v98, v99
	s_waitcnt vmcnt(47)
	global_store_dword v105, v104, s[76:77] offset:-3072
	v_lshlrev_b32_e32 v102, 16, v188
	v_and_b32_e32 v103, 0xffff0000, v188
	v_lshlrev_b32_e32 v96, 16, v172
	v_and_b32_e32 v97, 0xffff0000, v172
	v_pk_add_f32 v[96:97], v[102:103], v[96:97] neg_lo:[0,1] neg_hi:[0,1]
	v_pk_add_f32 v[100:101], v[100:101], v[96:97]
	s_cmp_eq_u32 s64, 0
	s_cbranch_scc1 .Lmx_ps3_1
	v_pk_mul_f32 v[98:99], v[100:101], s[72:73] op_sel_hi:[1,0]
.Lmx_pb3_1:
	v_pk_add_f32 v[98:99], v[98:99], v[102:103] neg_lo:[0,1] neg_hi:[0,1]
	v_cvt_pk_bf16_f32 v239, v98, v99
	global_store_dword v105, v239, s[76:77] offset:-1024
	v_lshlrev_b32_e32 v102, 16, v189
	v_and_b32_e32 v103, 0xffff0000, v189
	v_lshlrev_b32_e32 v96, 16, v173
	v_and_b32_e32 v97, 0xffff0000, v173
	v_pk_add_f32 v[96:97], v[102:103], v[96:97] neg_lo:[0,1] neg_hi:[0,1]
	v_pk_add_f32 v[100:101], v[100:101], v[96:97]
	s_cmp_eq_u32 s64, 0
	s_cbranch_scc1 .Lmx_ps3_2
	v_pk_mul_f32 v[98:99], v[100:101], s[72:73] op_sel_hi:[1,0]
.Lmx_pb3_2:
	v_pk_add_f32 v[98:99], v[98:99], v[102:103] neg_lo:[0,1] neg_hi:[0,1]
	v_cvt_pk_bf16_f32 v240, v98, v99
	global_store_dword v105, v240, s[76:77] offset:1024
	v_lshlrev_b32_e32 v102, 16, v190
	v_and_b32_e32 v103, 0xffff0000, v190
	v_lshlrev_b32_e32 v96, 16, v174
	v_and_b32_e32 v97, 0xffff0000, v174
	v_pk_add_f32 v[96:97], v[102:103], v[96:97] neg_lo:[0,1] neg_hi:[0,1]
	v_pk_add_f32 v[100:101], v[100:101], v[96:97]
	s_cmp_eq_u32 s64, 0
	s_cbranch_scc1 .Lmx_ps3_3
	v_pk_mul_f32 v[98:99], v[100:101], s[72:73] op_sel_hi:[1,0]
.Lmx_pb3_3:
	v_pk_add_f32 v[98:99], v[98:99], v[102:103] neg_lo:[0,1] neg_hi:[0,1]
	v_cvt_pk_bf16_f32 v241, v98, v99
	global_store_dword v105, v241, s[76:77] offset:3072
	v_lshlrev_b32_e32 v102, 16, v191
	v_and_b32_e32 v103, 0xffff0000, v191
	v_lshlrev_b32_e32 v96, 16, v175
	v_and_b32_e32 v97, 0xffff0000, v175
	v_pk_add_f32 v[96:97], v[102:103], v[96:97] neg_lo:[0,1] neg_hi:[0,1]
	v_pk_add_f32 v[100:101], v[100:101], v[96:97]
	s_cmp_eq_u32 s64, 0
	s_cbranch_scc1 .Lmx_ps3_4
	v_pk_mul_f32 v[98:99], v[100:101], s[72:73] op_sel_hi:[1,0]
.Lmx_pb3_4:
	v_pk_add_f32 v[98:99], v[98:99], v[102:103] neg_lo:[0,1] neg_hi:[0,1]
	v_cvt_pk_bf16_f32 v104, v98, v99
	s_add_u32 s76, s76, 0x2000
	s_addc_u32 s77, s77, 0
	global_store_dword v105, v104, s[76:77] offset:-3072
	v_lshlrev_b32_e32 v102, 16, v78
	v_and_b32_e32 v103, 0xffff0000, v78
	v_lshlrev_b32_e32 v96, 16, v176
	v_and_b32_e32 v97, 0xffff0000, v176
	v_pk_add_f32 v[96:97], v[102:103], v[96:97] neg_lo:[0,1] neg_hi:[0,1]
	v_pk_add_f32 v[100:101], v[100:101], v[96:97]
	s_cmp_eq_u32 s64, 0
	s_cbranch_scc1 .Lmx_ps3_5
	v_pk_mul_f32 v[98:99], v[100:101], s[72:73] op_sel_hi:[1,0]
; __device__ __forceinline__ unsigned pk2(float lo, float hi) { f32x2v v = {lo, hi}; b16x2v b = __builtin_convertvector(v, b16x2v); return __builtin_bit_cast(unsigned, b); }
; __device__ __forceinline__ f32x2v bf2(unsigned v) { return (f32x2v){bflo(v), bfhi(v)}; }
; template <int W>
; __device__ __forceinline__ void pool_prompt_w(const unsigned (&pin)[31], int t0, unsigned* dst  ) {
;     f32x2v s = {0.f, 0.f};
; #pragma unroll
;     for (int i = 0; i < W; ++i) s = s + bf2(pin[15 - i]);
; #pragma unroll
;     for (int t = 0; t < 16; ++t) {
;         if (t > 0) s = s + (bf2(pin[15 + t]) - bf2(pin[15 + t - W]));
;         const float cnt = (float)min(t0 + t + 1, W); const f32x2v cur = bf2(pin[15 + t]);
;         dst[(size_t)t * 512] = pk2(s.x / cnt - cur.x, s.y / cnt - cur.y);
.Lmx_pb3_5:
	v_pk_add_f32 v[98:99], v[98:99], v[102:103] neg_lo:[0,1] neg_hi:[0,1]
	v_cvt_pk_bf16_f32 v239, v98, v99
	global_store_dword v105, v239, s[76:77] offset:-1024
	v_lshlrev_b32_e32 v102, 16, v79
	v_and_b32_e32 v103, 0xffff0000, v79
	v_lshlrev_b32_e32 v96, 16, v177
	v_and_b32_e32 v97, 0xffff0000, v177
	v_pk_add_f32 v[96:97], v[102:103], v[96:97] neg_lo:[0,1] neg_hi:[0,1]
	v_pk_add_f32 v[100:101], v[100:101], v[96:97]
	s_cmp_eq_u32 s64, 0
	s_cbranch_scc1 .Lmx_ps3_6
	v_pk_mul_f32 v[98:99], v[100:101], s[72:73] op_sel_hi:[1,0]
.Lmx_pb3_6:
	v_pk_add_f32 v[98:99], v[98:99], v[102:103] neg_lo:[0,1] neg_hi:[0,1]
	v_cvt_pk_bf16_f32 v240, v98, v99
	global_store_dword v105, v240, s[76:77] offset:1024
	v_lshlrev_b32_e32 v102, 16, v80
	v_and_b32_e32 v103, 0xffff0000, v80
	v_lshlrev_b32_e32 v96, 16, v178
	v_and_b32_e32 v97, 0xffff0000, v178
	v_pk_add_f32 v[96:97], v[102:103], v[96:97] neg_lo:[0,1] neg_hi:[0,1]
	v_pk_add_f32 v[100:101], v[100:101], v[96:97]
	s_cmp_eq_u32 s64, 0
	s_cbranch_scc1 .Lmx_ps3_7
	v_pk_mul_f32 v[98:99], v[100:101], s[72:73] op_sel_hi:[1,0]
.Lmx_pb3_7:
	v_pk_add_f32 v[98:99], v[98:99], v[102:103] neg_lo:[0,1] neg_hi:[0,1]
	v_cvt_pk_bf16_f32 v241, v98, v99
	global_store_dword v105, v241, s[76:77] offset:3072
	v_lshlrev_b32_e32 v102, 16, v81
	v_and_b32_e32 v103, 0xffff0000, v81
	v_lshlrev_b32_e32 v96, 16, v179
	v_and_b32_e32 v97, 0xffff0000, v179
	v_pk_add_f32 v[96:97], v[102:103], v[96:97] neg_lo:[0,1] neg_hi:[0,1]
	v_pk_add_f32 v[100:101], v[100:101], v[96:97]
	s_cmp_eq_u32 s64, 0
	s_cbranch_scc1 .Lmx_ps3_8
	v_pk_mul_f32 v[98:99], v[100:101], s[72:73] op_sel_hi:[1,0]
.Lmx_pb3_8:
	v_pk_add_f32 v[98:99], v[98:99], v[102:103] neg_lo:[0,1] neg_hi:[0,1]
	v_cvt_pk_bf16_f32 v104, v98, v99
	s_add_u32 s76, s76, 0x2000
	s_addc_u32 s77, s77, 0
	global_store_dword v105, v104, s[76:77] offset:-3072
	v_lshlrev_b32_e32 v102, 16, v82
	v_and_b32_e32 v103, 0xffff0000, v82
	v_lshlrev_b32_e32 v96, 16, v180
	v_and_b32_e32 v97, 0xffff0000, v180
	v_pk_add_f32 v[96:97], v[102:103], v[96:97] neg_lo:[0,1] neg_hi:[0,1]
	v_pk_add_f32 v[100:101], v[100:101], v[96:97]
	s_cmp_eq_u32 s64, 0
	s_cbranch_scc1 .Lmx_ps3_9
	v_pk_mul_f32 v[98:99], v[100:101], s[72:73] op_sel_hi:[1,0]
.Lmx_pb3_9:
	v_pk_add_f32 v[98:99], v[98:99], v[102:103] neg_lo:[0,1] neg_hi:[0,1]
	v_cvt_pk_bf16_f32 v239, v98, v99
	global_store_dword v105, v239, s[76:77] offset:-1024
	v_lshlrev_b32_e32 v102, 16, v83
	v_and_b32_e32 v103, 0xffff0000, v83
	v_lshlrev_b32_e32 v96, 16, v181
	v_and_b32_e32 v97, 0xffff0000, v181
	v_pk_add_f32 v[96:97], v[102:103], v[96:97] neg_lo:[0,1] neg_hi:[0,1]
	v_pk_add_f32 v[100:101], v[100:101], v[96:97]
	s_cmp_eq_u32 s64, 0
	s_cbranch_scc1 .Lmx_ps3_10
	v_pk_mul_f32 v[98:99], v[100:101], s[72:73] op_sel_hi:[1,0]
.Lmx_pb3_10:
	v_pk_add_f32 v[98:99], v[98:99], v[102:103] neg_lo:[0,1] neg_hi:[0,1]
	v_cvt_pk_bf16_f32 v240, v98, v99
	global_store_dword v105, v240, s[76:77] offset:1024
	v_lshlrev_b32_e32 v102, 16, v84
	v_and_b32_e32 v103, 0xffff0000, v84
	v_lshlrev_b32_e32 v96, 16, v182
	v_and_b32_e32 v97, 0xffff0000, v182
	v_pk_add_f32 v[96:97], v[102:103], v[96:97] neg_lo:[0,1] neg_hi:[0,1]
	v_pk_add_f32 v[100:101], v[100:101], v[96:97]
	s_cmp_eq_u32 s64, 0
	s_cbranch_scc1 .Lmx_ps3_11
	v_pk_mul_f32 v[98:99], v[100:101], s[72:73] op_sel_hi:[1,0]
.Lmx_pb3_11:
	v_pk_add_f32 v[98:99], v[98:99], v[102:103] neg_lo:[0,1] neg_hi:[0,1]
	v_cvt_pk_bf16_f32 v241, v98, v99
	global_store_dword v105, v241, s[76:77] offset:3072
	v_lshlrev_b32_e32 v102, 16, v85
	v_and_b32_e32 v103, 0xffff0000, v85
	v_lshlrev_b32_e32 v96, 16, v183
	v_and_b32_e32 v97, 0xffff0000, v183
	v_pk_add_f32 v[96:97], v[102:103], v[96:97] neg_lo:[0,1] neg_hi:[0,1]
	v_pk_add_f32 v[100:101], v[100:101], v[96:97]
	s_cmp_eq_u32 s64, 0
	s_cbranch_scc1 .Lmx_ps3_12
	v_pk_mul_f32 v[98:99], v[100:101], s[72:73] op_sel_hi:[1,0]
.Lmx_pb3_12:
	v_pk_add_f32 v[98:99], v[98:99], v[102:103] neg_lo:[0,1] neg_hi:[0,1]
	v_cvt_pk_bf16_f32 v104, v98, v99
	s_add_u32 s76, s76, 0x2000
	s_addc_u32 s77, s77, 0
	global_store_dword v105, v104, s[76:77] offset:-3072
	v_lshlrev_b32_e32 v102, 16, v86
	v_and_b32_e32 v103, 0xffff0000, v86
	v_lshlrev_b32_e32 v96, 16, v184
	v_and_b32_e32 v97, 0xffff0000, v184
	v_pk_add_f32 v[96:97], v[102:103], v[96:97] neg_lo:[0,1] neg_hi:[0,1]
	v_pk_add_f32 v[100:101], v[100:101], v[96:97]
	s_cmp_eq_u32 s64, 0
	s_cbranch_scc1 .Lmx_ps3_13
	v_pk_mul_f32 v[98:99], v[100:101], s[72:73] op_sel_hi:[1,0]
.Lmx_pb3_13:
	v_pk_add_f32 v[98:99], v[98:99], v[102:103] neg_lo:[0,1] neg_hi:[0,1]
	v_cvt_pk_bf16_f32 v239, v98, v99
	global_store_dword v105, v239, s[76:77] offset:-1024
	v_lshlrev_b32_e32 v102, 16, v87
	v_and_b32_e32 v103, 0xffff0000, v87
	v_lshlrev_b32_e32 v96, 16, v185
	v_and_b32_e32 v97, 0xffff0000, v185
	v_pk_add_f32 v[96:97], v[102:103], v[96:97] neg_lo:[0,1] neg_hi:[0,1]
	v_pk_add_f32 v[100:101], v[100:101], v[96:97]
	s_cmp_eq_u32 s64, 0
	s_cbranch_scc1 .Lmx_ps3_14
	v_pk_mul_f32 v[98:99], v[100:101], s[72:73] op_sel_hi:[1,0]
.Lmx_pb3_14:
	v_pk_add_f32 v[98:99], v[98:99], v[102:103] neg_lo:[0,1] neg_hi:[0,1]
	v_cvt_pk_bf16_f32 v240, v98, v99
	global_store_dword v105, v240, s[76:77] offset:1024
	v_lshlrev_b32_e32 v102, 16, v88
	v_and_b32_e32 v103, 0xffff0000, v88
	v_lshlrev_b32_e32 v96, 16, v186
	v_and_b32_e32 v97, 0xffff0000, v186
	v_pk_add_f32 v[96:97], v[102:103], v[96:97] neg_lo:[0,1] neg_hi:[0,1]
	v_pk_add_f32 v[100:101], v[100:101], v[96:97]
	v_pk_mul_f32 v[98:99], v[100:101], s[72:73] op_sel_hi:[1,0]
	v_pk_add_f32 v[98:99], v[98:99], v[102:103] neg_lo:[0,1] neg_hi:[0,1]
	v_cvt_pk_bf16_f32 v241, v98, v99
	global_store_dword v105, v241, s[76:77] offset:3072
	s_branch .Lmx_pool_done

; __device__ __forceinline__ unsigned pk2(float lo, float hi) { f32x2v v = {lo, hi}; b16x2v b = __builtin_convertvector(v, b16x2v); return __builtin_bit_cast(unsigned, b); }
; __device__ __forceinline__ f32x2v bf2(unsigned v) { return (f32x2v){bflo(v), bfhi(v)}; }
; template <int W>
; __device__ __forceinline__ void pool_prompt_w(const unsigned (&pin)[31], int t0, unsigned* dst  ) {
;     f32x2v s = {0.f, 0.f};
; #pragma unroll
;     for (int i = 0; i < W; ++i) s = s + bf2(pin[15 - i]);
; #pragma unroll
;     for (int t = 0; t < 16; ++t) {
;         if (t > 0) s = s + (bf2(pin[15 + t]) - bf2(pin[15 + t - W]));
;         const float cnt = (float)min(t0 + t + 1, W); const f32x2v cur = bf2(pin[15 + t]);
;         dst[(size_t)t * 512] = pk2(s.x / cnt - cur.x, s.y / cnt - cur.y);
.Lmx_ps3_7:
	s_mov_b32 s78, 0x41000000
	s_mov_b32 s79, 0x3e000000
	v_mul_f32_e32 v98, s79, v100
	v_fma_f32 v96, -v98, s78, v100
	v_fma_f32 v98, v96, s79, v98
	v_mul_f32_e32 v99, s79, v101
	v_fma_f32 v96, -v99, s78, v101
	v_fma_f32 v99, v96, s79, v99
	s_branch .Lmx_pb3_7
.Lmx_ps3_8:
	s_mov_b32 s78, 0x41100000
	s_mov_b32 s79, 0x3de38e39
	v_mul_f32_e32 v98, s79, v100
	v_fma_f32 v96, -v98, s78, v100
	v_fma_f32 v98, v96, s79, v98
	v_mul_f32_e32 v99, s79, v101
	v_fma_f32 v96, -v99, s78, v101
	v_fma_f32 v99, v96, s79, v99
	s_branch .Lmx_pb3_8
.Lmx_ps3_9:
	s_mov_b32 s78, 0x41200000
	s_mov_b32 s79, 0x3dcccccd
	v_mul_f32_e32 v98, s79, v100
	v_fma_f32 v96, -v98, s78, v100
	v_fma_f32 v98, v96, s79, v98
	v_mul_f32_e32 v99, s79, v101
	v_fma_f32 v96, -v99, s78, v101
	v_fma_f32 v99, v96, s79, v99
	s_branch .Lmx_pb3_9
.Lmx_ps3_10:
	s_mov_b32 s78, 0x41300000
	s_mov_b32 s79, 0x3dba2e8c
	v_mul_f32_e32 v98, s79, v100
	v_fma_f32 v96, -v98, s78, v100
	v_fma_f32 v98, v96, s79, v98
	v_mul_f32_e32 v99, s79, v101
	v_fma_f32 v96, -v99, s78, v101
	v_fma_f32 v99, v96, s79, v99
	s_branch .Lmx_pb3_10
.Lmx_ps3_11:
	s_mov_b32 s78, 0x41400000
	s_mov_b32 s79, 0x3daaaaab
	v_mul_f32_e32 v98, s79, v100
	v_fma_f32 v96, -v98, s78, v100
	v_fma_f32 v98, v96, s79, v98
	v_mul_f32_e32 v99, s79, v101
	v_fma_f32 v96, -v99, s78, v101
	v_fma_f32 v99, v96, s79, v99
	s_branch .Lmx_pb3_11
.Lmx_ps3_12:
	s_mov_b32 s78, 0x41500000
	s_mov_b32 s79, 0x3d9d89d9
	v_mul_f32_e32 v98, s79, v100
	v_fma_f32 v96, -v98, s78, v100
	v_fma_f32 v98, v96, s79, v98
	v_mul_f32_e32 v99, s79, v101
	v_fma_f32 v96, -v99, s78, v101
	v_fma_f32 v99, v96, s79, v99
	s_branch .Lmx_pb3_12
.Lmx_ps3_13:
	s_mov_b32 s78, 0x41600000
	s_mov_b32 s79, 0x3d924925
	v_mul_f32_e32 v98, s79, v100
	v_fma_f32 v96, -v98, s78, v100
	v_fma_f32 v98, v96, s79, v98
	v_mul_f32_e32 v99, s79, v101
	v_fma_f32 v96, -v99, s78, v101
	v_fma_f32 v99, v96, s79, v99
	s_branch .Lmx_pb3_13
.Lmx_ps3_14:
	s_mov_b32 s78, 0x41700000
	s_mov_b32 s79, 0x3d888889
	v_mul_f32_e32 v98, s79, v100
	v_fma_f32 v96, -v98, s78, v100
	v_fma_f32 v98, v96, s79, v98
	v_mul_f32_e32 v99, s79, v101
	v_fma_f32 v96, -v99, s78, v101
	v_fma_f32 v99, v96, s79, v99
	s_branch .Lmx_pb3_14
.Lmx_pool_done:
	v_xor_b32_e32 v239, 16, v165
	v_lshlrev_b32_e32 v239, 2, v239
	s_waitcnt vmcnt(30)
	s_cbranch_vccnz .Lmx_e0

; __device__ __forceinline__ f32x2v bf2(unsigned v) { return (f32x2v){bflo(v), bfhi(v)}; }
; __device__ __forceinline__ void mixer_prompt_run(const Args& p, int run, int c2) {
;     ...
;             for (int i = 0; i < 38; ++i) {
;                 const int ti = t0 + 8 * hh - 30 + i; unsigned v = U32[(rowb + (ti >= 0 ? ti : 0)) * 256 + c2]; v = (ti >= 0) ? v : 0u; const f32x2v x = bf2(v);
; #pragma unroll
;                 for (int t = 0; t < 8; ++t) { const int j = i - t; if (j >= 0 && j <= 30) a[t] = w[j] * x + a[t]; }
;                 if (i == 18) asm volatile("" ::: "memory");
.Lmx_b14:
	v_lshlrev_b32_e32 v96, 16, v207
	v_and_b32_e32 v97, 0xffff0000, v207
	v_pk_fma_f32 v[172:173], v[134:135], v[96:97], v[172:173]
	v_pk_fma_f32 v[174:175], v[132:133], v[96:97], v[174:175]
	v_pk_fma_f32 v[176:177], v[130:131], v[96:97], v[176:177]
	v_pk_fma_f32 v[178:179], v[128:129], v[96:97], v[178:179]
	v_pk_fma_f32 v[180:181], v[126:127], v[96:97], v[180:181]
	v_pk_fma_f32 v[182:183], v[124:125], v[96:97], v[182:183]
	v_pk_fma_f32 v[184:185], v[122:123], v[96:97], v[184:185]
	v_pk_fma_f32 v[186:187], v[120:121], v[96:97], v[186:187]
	v_pk_fma_f32 v[188:189], v[118:119], v[96:97], v[188:189]
	v_pk_fma_f32 v[190:191], v[116:117], v[96:97], v[190:191]
	v_pk_fma_f32 v[78:79], v[114:115], v[96:97], v[78:79]
	v_pk_fma_f32 v[80:81], v[112:113], v[96:97], v[80:81]
	v_pk_fma_f32 v[82:83], v[110:111], v[96:97], v[82:83]
	v_pk_fma_f32 v[84:85], v[108:109], v[96:97], v[84:85]
	v_pk_fma_f32 v[86:87], v[106:107], v[96:97], v[90:91]
	s_cbranch_vccnz .Lmx_e15
.Lmx_b15:
	v_lshlrev_b32_e32 v98, 16, v208
	v_and_b32_e32 v99, 0xffff0000, v208
	v_pk_fma_f32 v[172:173], v[136:137], v[98:99], v[172:173]
	v_pk_fma_f32 v[174:175], v[134:135], v[98:99], v[174:175]
	v_pk_fma_f32 v[176:177], v[132:133], v[98:99], v[176:177]
	v_pk_fma_f32 v[178:179], v[130:131], v[98:99], v[178:179]
	v_pk_fma_f32 v[180:181], v[128:129], v[98:99], v[180:181]
	v_pk_fma_f32 v[182:183], v[126:127], v[98:99], v[182:183]
	v_pk_fma_f32 v[184:185], v[124:125], v[98:99], v[184:185]
	v_pk_fma_f32 v[186:187], v[122:123], v[98:99], v[186:187]
	v_pk_fma_f32 v[188:189], v[120:121], v[98:99], v[188:189]
	v_pk_fma_f32 v[190:191], v[118:119], v[98:99], v[190:191]
	v_pk_fma_f32 v[78:79], v[116:117], v[98:99], v[78:79]
	v_pk_fma_f32 v[80:81], v[114:115], v[98:99], v[80:81]
	v_pk_fma_f32 v[82:83], v[112:113], v[98:99], v[82:83]
	v_pk_fma_f32 v[84:85], v[110:111], v[98:99], v[84:85]
	v_pk_fma_f32 v[86:87], v[108:109], v[98:99], v[86:87]
	v_pk_fma_f32 v[88:89], v[106:107], v[98:99], v[90:91]
	s_cbranch_vccnz .Lmx_e16
.Lmx_b16:
	v_lshlrev_b32_e32 v96, 16, v209
	v_and_b32_e32 v97, 0xffff0000, v209
	v_pk_fma_f32 v[172:173], v[138:139], v[96:97], v[172:173]
	v_pk_fma_f32 v[174:175], v[136:137], v[96:97], v[174:175]
	v_pk_fma_f32 v[176:177], v[134:135], v[96:97], v[176:177]
	v_pk_fma_f32 v[178:179], v[132:133], v[96:97], v[178:179]
	v_pk_fma_f32 v[180:181], v[130:131], v[96:97], v[180:181]
	v_pk_fma_f32 v[182:183], v[128:129], v[96:97], v[182:183]
	v_pk_fma_f32 v[184:185], v[126:127], v[96:97], v[184:185]
	v_pk_fma_f32 v[186:187], v[124:125], v[96:97], v[186:187]
	v_pk_fma_f32 v[188:189], v[122:123], v[96:97], v[188:189]
	v_pk_fma_f32 v[190:191], v[120:121], v[96:97], v[190:191]
	v_pk_fma_f32 v[78:79], v[118:119], v[96:97], v[78:79]
	v_pk_fma_f32 v[80:81], v[116:117], v[96:97], v[80:81]
	v_pk_fma_f32 v[82:83], v[114:115], v[96:97], v[82:83]
	v_pk_fma_f32 v[84:85], v[112:113], v[96:97], v[84:85]
	v_pk_fma_f32 v[86:87], v[110:111], v[96:97], v[86:87]
	v_pk_fma_f32 v[88:89], v[108:109], v[96:97], v[88:89]
	s_cbranch_vccnz .Lmx_e17
.Lmx_b17:
	v_lshlrev_b32_e32 v98, 16, v210
	v_and_b32_e32 v99, 0xffff0000, v210
	v_pk_fma_f32 v[172:173], v[140:141], v[98:99], v[172:173]
	v_pk_fma_f32 v[174:175], v[138:139], v[98:99], v[174:175]
	v_pk_fma_f32 v[176:177], v[136:137], v[98:99], v[176:177]
	v_pk_fma_f32 v[178:179], v[134:135], v[98:99], v[178:179]
	v_pk_fma_f32 v[180:181], v[132:133], v[98:99], v[180:181]
	v_pk_fma_f32 v[182:183], v[130:131], v[98:99], v[182:183]
	v_pk_fma_f32 v[184:185], v[128:129], v[98:99], v[184:185]
	v_pk_fma_f32 v[186:187], v[126:127], v[98:99], v[186:187]
	v_pk_fma_f32 v[188:189], v[124:125], v[98:99], v[188:189]
	v_pk_fma_f32 v[190:191], v[122:123], v[98:99], v[190:191]
	v_pk_fma_f32 v[78:79], v[120:121], v[98:99], v[78:79]
	v_pk_fma_f32 v[80:81], v[118:119], v[98:99], v[80:81]
	v_pk_fma_f32 v[82:83], v[116:117], v[98:99], v[82:83]
	v_pk_fma_f32 v[84:85], v[114:115], v[98:99], v[84:85]
	v_pk_fma_f32 v[86:87], v[112:113], v[98:99], v[86:87]
	v_pk_fma_f32 v[88:89], v[110:111], v[98:99], v[88:89]
	s_cbranch_vccnz .Lmx_e18
.Lmx_b18:
	v_lshlrev_b32_e32 v96, 16, v211
	v_and_b32_e32 v97, 0xffff0000, v211
	v_pk_fma_f32 v[172:173], v[142:143], v[96:97], v[172:173]
	v_pk_fma_f32 v[174:175], v[140:141], v[96:97], v[174:175]
	v_pk_fma_f32 v[176:177], v[138:139], v[96:97], v[176:177]
	v_pk_fma_f32 v[178:179], v[136:137], v[96:97], v[178:179]
	v_pk_fma_f32 v[180:181], v[134:135], v[96:97], v[180:181]
	v_pk_fma_f32 v[182:183], v[132:133], v[96:97], v[182:183]
	v_pk_fma_f32 v[184:185], v[130:131], v[96:97], v[184:185]
	v_pk_fma_f32 v[186:187], v[128:129], v[96:97], v[186:187]
	v_pk_fma_f32 v[188:189], v[126:127], v[96:97], v[188:189]
	v_pk_fma_f32 v[190:191], v[124:125], v[96:97], v[190:191]
	v_pk_fma_f32 v[78:79], v[122:123], v[96:97], v[78:79]
	v_pk_fma_f32 v[80:81], v[120:121], v[96:97], v[80:81]
	v_pk_fma_f32 v[82:83], v[118:119], v[96:97], v[82:83]
	v_pk_fma_f32 v[84:85], v[116:117], v[96:97], v[84:85]
	v_pk_fma_f32 v[86:87], v[114:115], v[96:97], v[86:87]
	v_pk_fma_f32 v[88:89], v[112:113], v[96:97], v[88:89]
	s_cbranch_vccnz .Lmx_e19
.Lmx_b19:
	v_lshlrev_b32_e32 v98, 16, v212
	v_and_b32_e32 v99, 0xffff0000, v212
	v_pk_fma_f32 v[172:173], v[144:145], v[98:99], v[172:173]
	v_pk_fma_f32 v[174:175], v[142:143], v[98:99], v[174:175]
	v_pk_fma_f32 v[176:177], v[140:141], v[98:99], v[176:177]
	v_pk_fma_f32 v[178:179], v[138:139], v[98:99], v[178:179]
	v_pk_fma_f32 v[180:181], v[136:137], v[98:99], v[180:181]
	v_pk_fma_f32 v[182:183], v[134:135], v[98:99], v[182:183]
	v_pk_fma_f32 v[184:185], v[132:133], v[98:99], v[184:185]
	v_pk_fma_f32 v[186:187], v[130:131], v[98:99], v[186:187]
	v_pk_fma_f32 v[188:189], v[128:129], v[98:99], v[188:189]
	v_pk_fma_f32 v[190:191], v[126:127], v[98:99], v[190:191]
	v_pk_fma_f32 v[78:79], v[124:125], v[98:99], v[78:79]
	v_pk_fma_f32 v[80:81], v[122:123], v[98:99], v[80:81]
	v_pk_fma_f32 v[82:83], v[120:121], v[98:99], v[82:83]
	v_pk_fma_f32 v[84:85], v[118:119], v[98:99], v[84:85]
	v_pk_fma_f32 v[86:87], v[116:117], v[98:99], v[86:87]
	v_pk_fma_f32 v[88:89], v[114:115], v[98:99], v[88:89]
	s_cbranch_vccnz .Lmx_e20
; __device__ __forceinline__ f32x2v bf2(unsigned v) { return (f32x2v){bflo(v), bfhi(v)}; }
; __device__ __forceinline__ void mixer_prompt_run(const Args& p, int run, int c2) {
;     ...
;             for (int i = 0; i < 38; ++i) {
;                 const int ti = t0 + 8 * hh - 30 + i; unsigned v = U32[(rowb + (ti >= 0 ? ti : 0)) * 256 + c2]; v = (ti >= 0) ? v : 0u; const f32x2v x = bf2(v);
; #pragma unroll
;                 for (int t = 0; t < 8; ++t) { const int j = i - t; if (j >= 0 && j <= 30) a[t] = w[j] * x + a[t]; }
;                 if (i == 18) asm volatile("" ::: "memory");
.Lmx_b20:
	v_lshlrev_b32_e32 v96, 16, v213
	v_and_b32_e32 v97, 0xffff0000, v213
	v_pk_fma_f32 v[172:173], v[146:147], v[96:97], v[172:173]
	v_pk_fma_f32 v[174:175], v[144:145], v[96:97], v[174:175]
	v_pk_fma_f32 v[176:177], v[142:143], v[96:97], v[176:177]
	v_pk_fma_f32 v[178:179], v[140:141], v[96:97], v[178:179]
	v_pk_fma_f32 v[180:181], v[138:139], v[96:97], v[180:181]
	v_pk_fma_f32 v[182:183], v[136:137], v[96:97], v[182:183]
	v_pk_fma_f32 v[184:185], v[134:135], v[96:97], v[184:185]
	v_pk_fma_f32 v[186:187], v[132:133], v[96:97], v[186:187]
	v_pk_fma_f32 v[188:189], v[130:131], v[96:97], v[188:189]
	v_pk_fma_f32 v[190:191], v[128:129], v[96:97], v[190:191]
	v_pk_fma_f32 v[78:79], v[126:127], v[96:97], v[78:79]
	v_pk_fma_f32 v[80:81], v[124:125], v[96:97], v[80:81]
	v_pk_fma_f32 v[82:83], v[122:123], v[96:97], v[82:83]
	v_pk_fma_f32 v[84:85], v[120:121], v[96:97], v[84:85]
	v_pk_fma_f32 v[86:87], v[118:119], v[96:97], v[86:87]
	v_pk_fma_f32 v[88:89], v[116:117], v[96:97], v[88:89]
	s_cbranch_vccnz .Lmx_e21
.Lmx_b21:
	v_lshlrev_b32_e32 v98, 16, v214
	v_and_b32_e32 v99, 0xffff0000, v214
	v_pk_fma_f32 v[172:173], v[148:149], v[98:99], v[172:173]
	v_pk_fma_f32 v[174:175], v[146:147], v[98:99], v[174:175]
	v_pk_fma_f32 v[176:177], v[144:145], v[98:99], v[176:177]
	v_pk_fma_f32 v[178:179], v[142:143], v[98:99], v[178:179]
	v_pk_fma_f32 v[180:181], v[140:141], v[98:99], v[180:181]
	v_pk_fma_f32 v[182:183], v[138:139], v[98:99], v[182:183]
	v_pk_fma_f32 v[184:185], v[136:137], v[98:99], v[184:185]
	v_pk_fma_f32 v[186:187], v[134:135], v[98:99], v[186:187]
	v_pk_fma_f32 v[188:189], v[132:133], v[98:99], v[188:189]
	v_pk_fma_f32 v[190:191], v[130:131], v[98:99], v[190:191]
	v_pk_fma_f32 v[78:79], v[128:129], v[98:99], v[78:79]
	v_pk_fma_f32 v[80:81], v[126:127], v[98:99], v[80:81]
	v_pk_fma_f32 v[82:83], v[124:125], v[98:99], v[82:83]
	v_pk_fma_f32 v[84:85], v[122:123], v[98:99], v[84:85]
	v_pk_fma_f32 v[86:87], v[120:121], v[98:99], v[86:87]
	v_pk_fma_f32 v[88:89], v[118:119], v[98:99], v[88:89]
	s_cbranch_vccnz .Lmx_e22
.Lmx_b22:
	v_lshlrev_b32_e32 v96, 16, v215
	v_and_b32_e32 v97, 0xffff0000, v215
	v_pk_fma_f32 v[172:173], v[150:151], v[96:97], v[172:173]
	v_pk_fma_f32 v[174:175], v[148:149], v[96:97], v[174:175]
	v_pk_fma_f32 v[176:177], v[146:147], v[96:97], v[176:177]
	v_pk_fma_f32 v[178:179], v[144:145], v[96:97], v[178:179]
	v_pk_fma_f32 v[180:181], v[142:143], v[96:97], v[180:181]
	v_pk_fma_f32 v[182:183], v[140:141], v[96:97], v[182:183]
	v_pk_fma_f32 v[184:185], v[138:139], v[96:97], v[184:185]
	v_pk_fma_f32 v[186:187], v[136:137], v[96:97], v[186:187]
	v_pk_fma_f32 v[188:189], v[134:135], v[96:97], v[188:189]
	v_pk_fma_f32 v[190:191], v[132:133], v[96:97], v[190:191]
	v_pk_fma_f32 v[78:79], v[130:131], v[96:97], v[78:79]
	v_pk_fma_f32 v[80:81], v[128:129], v[96:97], v[80:81]
	v_pk_fma_f32 v[82:83], v[126:127], v[96:97], v[82:83]
	v_pk_fma_f32 v[84:85], v[124:125], v[96:97], v[84:85]
	v_pk_fma_f32 v[86:87], v[122:123], v[96:97], v[86:87]
	v_pk_fma_f32 v[88:89], v[120:121], v[96:97], v[88:89]
	s_cbranch_vccnz .Lmx_e23
.Lmx_b23:
	v_lshlrev_b32_e32 v98, 16, v216
	v_and_b32_e32 v99, 0xffff0000, v216
	v_pk_fma_f32 v[172:173], v[152:153], v[98:99], v[172:173]
	v_pk_fma_f32 v[174:175], v[150:151], v[98:99], v[174:175]
	v_pk_fma_f32 v[176:177], v[148:149], v[98:99], v[176:177]
	v_pk_fma_f32 v[178:179], v[146:147], v[98:99], v[178:179]
	v_pk_fma_f32 v[180:181], v[144:145], v[98:99], v[180:181]
	v_pk_fma_f32 v[182:183], v[142:143], v[98:99], v[182:183]
	v_pk_fma_f32 v[184:185], v[140:141], v[98:99], v[184:185]
	v_pk_fma_f32 v[186:187], v[138:139], v[98:99], v[186:187]
	v_pk_fma_f32 v[188:189], v[136:137], v[98:99], v[188:189]
	v_pk_fma_f32 v[190:191], v[134:135], v[98:99], v[190:191]
	v_pk_fma_f32 v[78:79], v[132:133], v[98:99], v[78:79]
	v_pk_fma_f32 v[80:81], v[130:131], v[98:99], v[80:81]
	v_pk_fma_f32 v[82:83], v[128:129], v[98:99], v[82:83]
	v_pk_fma_f32 v[84:85], v[126:127], v[98:99], v[84:85]
	v_pk_fma_f32 v[86:87], v[124:125], v[98:99], v[86:87]
	v_pk_fma_f32 v[88:89], v[122:123], v[98:99], v[88:89]
	s_cbranch_vccnz .Lmx_e24
.Lmx_b24:
	v_lshlrev_b32_e32 v96, 16, v217
	v_and_b32_e32 v97, 0xffff0000, v217
	v_pk_fma_f32 v[172:173], v[154:155], v[96:97], v[172:173]
	v_pk_fma_f32 v[174:175], v[152:153], v[96:97], v[174:175]
	v_pk_fma_f32 v[176:177], v[150:151], v[96:97], v[176:177]
	v_pk_fma_f32 v[178:179], v[148:149], v[96:97], v[178:179]
	v_pk_fma_f32 v[180:181], v[146:147], v[96:97], v[180:181]
	v_pk_fma_f32 v[182:183], v[144:145], v[96:97], v[182:183]
	v_pk_fma_f32 v[184:185], v[142:143], v[96:97], v[184:185]
	v_pk_fma_f32 v[186:187], v[140:141], v[96:97], v[186:187]
	v_pk_fma_f32 v[188:189], v[138:139], v[96:97], v[188:189]
	v_pk_fma_f32 v[190:191], v[136:137], v[96:97], v[190:191]
	v_pk_fma_f32 v[78:79], v[134:135], v[96:97], v[78:79]
	v_pk_fma_f32 v[80:81], v[132:133], v[96:97], v[80:81]
	v_pk_fma_f32 v[82:83], v[130:131], v[96:97], v[82:83]
	v_pk_fma_f32 v[84:85], v[128:129], v[96:97], v[84:85]
	v_pk_fma_f32 v[86:87], v[126:127], v[96:97], v[86:87]
	v_pk_fma_f32 v[88:89], v[124:125], v[96:97], v[88:89]
	s_cbranch_vccnz .Lmx_e25
; __device__ __forceinline__ f32x2v bf2(unsigned v) { return (f32x2v){bflo(v), bfhi(v)}; }
; __device__ __forceinline__ void mixer_prompt_run(const Args& p, int run, int c2) {
;     ...
;             for (int i = 0; i < 38; ++i) {
;                 const int ti = t0 + 8 * hh - 30 + i; unsigned v = U32[(rowb + (ti >= 0 ? ti : 0)) * 256 + c2]; v = (ti >= 0) ? v : 0u; const f32x2v x = bf2(v);
; #pragma unroll
;                 for (int t = 0; t < 8; ++t) { const int j = i - t; if (j >= 0 && j <= 30) a[t] = w[j] * x + a[t]; }
;                 if (i == 18) asm volatile("" ::: "memory");
.Lmx_b25:
	v_lshlrev_b32_e32 v98, 16, v218
	v_and_b32_e32 v99, 0xffff0000, v218
	v_pk_fma_f32 v[172:173], v[156:157], v[98:99], v[172:173]
	v_pk_fma_f32 v[174:175], v[154:155], v[98:99], v[174:175]
	v_pk_fma_f32 v[176:177], v[152:153], v[98:99], v[176:177]
	v_pk_fma_f32 v[178:179], v[150:151], v[98:99], v[178:179]
	v_pk_fma_f32 v[180:181], v[148:149], v[98:99], v[180:181]
	v_pk_fma_f32 v[182:183], v[146:147], v[98:99], v[182:183]
	v_pk_fma_f32 v[184:185], v[144:145], v[98:99], v[184:185]
	v_pk_fma_f32 v[186:187], v[142:143], v[98:99], v[186:187]
	v_pk_fma_f32 v[188:189], v[140:141], v[98:99], v[188:189]
	v_pk_fma_f32 v[190:191], v[138:139], v[98:99], v[190:191]
	v_pk_fma_f32 v[78:79], v[136:137], v[98:99], v[78:79]
	v_pk_fma_f32 v[80:81], v[134:135], v[98:99], v[80:81]
	v_pk_fma_f32 v[82:83], v[132:133], v[98:99], v[82:83]
	v_pk_fma_f32 v[84:85], v[130:131], v[98:99], v[84:85]
	v_pk_fma_f32 v[86:87], v[128:129], v[98:99], v[86:87]
	v_pk_fma_f32 v[88:89], v[126:127], v[98:99], v[88:89]
	s_cbranch_vccnz .Lmx_e26
.Lmx_b26:
	v_lshlrev_b32_e32 v96, 16, v219
	v_and_b32_e32 v97, 0xffff0000, v219
	v_pk_fma_f32 v[172:173], v[158:159], v[96:97], v[172:173]
	v_pk_fma_f32 v[174:175], v[156:157], v[96:97], v[174:175]
	v_pk_fma_f32 v[176:177], v[154:155], v[96:97], v[176:177]
	v_pk_fma_f32 v[178:179], v[152:153], v[96:97], v[178:179]
	v_pk_fma_f32 v[180:181], v[150:151], v[96:97], v[180:181]
	v_pk_fma_f32 v[182:183], v[148:149], v[96:97], v[182:183]
	v_pk_fma_f32 v[184:185], v[146:147], v[96:97], v[184:185]
	v_pk_fma_f32 v[186:187], v[144:145], v[96:97], v[186:187]
	v_pk_fma_f32 v[188:189], v[142:143], v[96:97], v[188:189]
	v_pk_fma_f32 v[190:191], v[140:141], v[96:97], v[190:191]
	v_pk_fma_f32 v[78:79], v[138:139], v[96:97], v[78:79]
	v_pk_fma_f32 v[80:81], v[136:137], v[96:97], v[80:81]
	v_pk_fma_f32 v[82:83], v[134:135], v[96:97], v[82:83]
	v_pk_fma_f32 v[84:85], v[132:133], v[96:97], v[84:85]
	v_pk_fma_f32 v[86:87], v[130:131], v[96:97], v[86:87]
	v_pk_fma_f32 v[88:89], v[128:129], v[96:97], v[88:89]
	s_cbranch_vccnz .Lmx_e27
.Lmx_b27:
	v_lshlrev_b32_e32 v98, 16, v220
	v_and_b32_e32 v99, 0xffff0000, v220
	v_pk_fma_f32 v[172:173], v[160:161], v[98:99], v[172:173]
	v_pk_fma_f32 v[174:175], v[158:159], v[98:99], v[174:175]
	v_pk_fma_f32 v[176:177], v[156:157], v[98:99], v[176:177]
	v_pk_fma_f32 v[178:179], v[154:155], v[98:99], v[178:179]
	v_pk_fma_f32 v[180:181], v[152:153], v[98:99], v[180:181]
	v_pk_fma_f32 v[182:183], v[150:151], v[98:99], v[182:183]
	v_pk_fma_f32 v[184:185], v[148:149], v[98:99], v[184:185]
	v_pk_fma_f32 v[186:187], v[146:147], v[98:99], v[186:187]
	v_pk_fma_f32 v[188:189], v[144:145], v[98:99], v[188:189]
	v_pk_fma_f32 v[190:191], v[142:143], v[98:99], v[190:191]
	v_pk_fma_f32 v[78:79], v[140:141], v[98:99], v[78:79]
	v_pk_fma_f32 v[80:81], v[138:139], v[98:99], v[80:81]
	v_pk_fma_f32 v[82:83], v[136:137], v[98:99], v[82:83]
	v_pk_fma_f32 v[84:85], v[134:135], v[98:99], v[84:85]
	v_pk_fma_f32 v[86:87], v[132:133], v[98:99], v[86:87]
	v_pk_fma_f32 v[88:89], v[130:131], v[98:99], v[88:89]
	s_cbranch_vccnz .Lmx_e28
.Lmx_b28:
	v_lshlrev_b32_e32 v96, 16, v221
	v_and_b32_e32 v97, 0xffff0000, v221
	v_pk_fma_f32 v[172:173], v[162:163], v[96:97], v[172:173]
	v_pk_fma_f32 v[174:175], v[160:161], v[96:97], v[174:175]
	v_pk_fma_f32 v[176:177], v[158:159], v[96:97], v[176:177]
	v_pk_fma_f32 v[178:179], v[156:157], v[96:97], v[178:179]
	v_pk_fma_f32 v[180:181], v[154:155], v[96:97], v[180:181]
	v_pk_fma_f32 v[182:183], v[152:153], v[96:97], v[182:183]
	v_pk_fma_f32 v[184:185], v[150:151], v[96:97], v[184:185]
	v_pk_fma_f32 v[186:187], v[148:149], v[96:97], v[186:187]
	v_pk_fma_f32 v[188:189], v[146:147], v[96:97], v[188:189]
	v_pk_fma_f32 v[190:191], v[144:145], v[96:97], v[190:191]
	v_pk_fma_f32 v[78:79], v[142:143], v[96:97], v[78:79]
	v_pk_fma_f32 v[80:81], v[140:141], v[96:97], v[80:81]
	v_pk_fma_f32 v[82:83], v[138:139], v[96:97], v[82:83]
	v_pk_fma_f32 v[84:85], v[136:137], v[96:97], v[84:85]
	v_pk_fma_f32 v[86:87], v[134:135], v[96:97], v[86:87]
	v_pk_fma_f32 v[88:89], v[132:133], v[96:97], v[88:89]
	s_cbranch_vccnz .Lmx_e29
.Lmx_b29:
	v_lshlrev_b32_e32 v98, 16, v222
	v_and_b32_e32 v99, 0xffff0000, v222
	v_pk_fma_f32 v[172:173], v[168:169], v[98:99], v[172:173]
	v_pk_fma_f32 v[174:175], v[162:163], v[98:99], v[174:175]
	v_pk_fma_f32 v[176:177], v[160:161], v[98:99], v[176:177]
	v_pk_fma_f32 v[178:179], v[158:159], v[98:99], v[178:179]
	v_pk_fma_f32 v[180:181], v[156:157], v[98:99], v[180:181]
	v_pk_fma_f32 v[182:183], v[154:155], v[98:99], v[182:183]
	v_pk_fma_f32 v[184:185], v[152:153], v[98:99], v[184:185]
	v_pk_fma_f32 v[186:187], v[150:151], v[98:99], v[186:187]
	v_pk_fma_f32 v[188:189], v[148:149], v[98:99], v[188:189]
	v_pk_fma_f32 v[190:191], v[146:147], v[98:99], v[190:191]
	v_pk_fma_f32 v[78:79], v[144:145], v[98:99], v[78:79]
	v_pk_fma_f32 v[80:81], v[142:143], v[98:99], v[80:81]
	v_pk_fma_f32 v[82:83], v[140:141], v[98:99], v[82:83]
	v_pk_fma_f32 v[84:85], v[138:139], v[98:99], v[84:85]
	v_pk_fma_f32 v[86:87], v[136:137], v[98:99], v[86:87]
	v_pk_fma_f32 v[88:89], v[134:135], v[98:99], v[88:89]
	v_lshlrev_b32_e32 v96, 16, v223
	v_and_b32_e32 v97, 0xffff0000, v223
	v_pk_fma_f32 v[172:173], v[170:171], v[96:97], v[172:173]
	v_pk_fma_f32 v[174:175], v[168:169], v[96:97], v[174:175]
	v_pk_fma_f32 v[176:177], v[162:163], v[96:97], v[176:177]
	v_pk_fma_f32 v[178:179], v[160:161], v[96:97], v[178:179]
	v_pk_fma_f32 v[180:181], v[158:159], v[96:97], v[180:181]
	v_pk_fma_f32 v[182:183], v[156:157], v[96:97], v[182:183]
	v_pk_fma_f32 v[184:185], v[154:155], v[96:97], v[184:185]
	v_pk_fma_f32 v[186:187], v[152:153], v[96:97], v[186:187]
	v_pk_fma_f32 v[188:189], v[150:151], v[96:97], v[188:189]
	v_pk_fma_f32 v[190:191], v[148:149], v[96:97], v[190:191]
	v_pk_fma_f32 v[78:79], v[146:147], v[96:97], v[78:79]
	v_pk_fma_f32 v[80:81], v[144:145], v[96:97], v[80:81]
	v_pk_fma_f32 v[82:83], v[142:143], v[96:97], v[82:83]
	v_pk_fma_f32 v[84:85], v[140:141], v[96:97], v[84:85]
	v_pk_fma_f32 v[86:87], v[138:139], v[96:97], v[86:87]
	v_pk_fma_f32 v[88:89], v[136:137], v[96:97], v[88:89]
	v_lshlrev_b32_e32 v98, 16, v224
	v_and_b32_e32 v99, 0xffff0000, v224
	v_pk_fma_f32 v[174:175], v[170:171], v[98:99], v[174:175]
	v_pk_fma_f32 v[176:177], v[168:169], v[98:99], v[176:177]
	v_pk_fma_f32 v[178:179], v[162:163], v[98:99], v[178:179]
	v_pk_fma_f32 v[180:181], v[160:161], v[98:99], v[180:181]
	v_pk_fma_f32 v[182:183], v[158:159], v[98:99], v[182:183]
	v_pk_fma_f32 v[184:185], v[156:157], v[98:99], v[184:185]
	v_pk_fma_f32 v[186:187], v[154:155], v[98:99], v[186:187]
	v_pk_fma_f32 v[188:189], v[152:153], v[98:99], v[188:189]
	v_pk_fma_f32 v[190:191], v[150:151], v[98:99], v[190:191]
	v_pk_fma_f32 v[78:79], v[148:149], v[98:99], v[78:79]
	v_pk_fma_f32 v[80:81], v[146:147], v[98:99], v[80:81]
	v_pk_fma_f32 v[82:83], v[144:145], v[98:99], v[82:83]
	v_pk_fma_f32 v[84:85], v[142:143], v[98:99], v[84:85]
	v_pk_fma_f32 v[86:87], v[140:141], v[98:99], v[86:87]
	v_pk_fma_f32 v[88:89], v[138:139], v[98:99], v[88:89]
	s_waitcnt vmcnt(29)
; __device__ __forceinline__ f32x2v bf2(unsigned v) { return (f32x2v){bflo(v), bfhi(v)}; }
; __device__ __forceinline__ void mixer_prompt_run(const Args& p, int run, int c2) {
;     ...
;             for (int i = 0; i < 38; ++i) {
;                 const int ti = t0 + 8 * hh - 30 + i; unsigned v = U32[(rowb + (ti >= 0 ? ti : 0)) * 256 + c2]; v = (ti >= 0) ? v : 0u; const f32x2v x = bf2(v);
; #pragma unroll
;                 for (int t = 0; t < 8; ++t) { const int j = i - t; if (j >= 0 && j <= 30) a[t] = w[j] * x + a[t]; }
;                 if (i == 18) asm volatile("" ::: "memory");
	v_lshlrev_b32_e32 v96, 16, v225
	v_and_b32_e32 v97, 0xffff0000, v225
	v_pk_fma_f32 v[176:177], v[170:171], v[96:97], v[176:177]
	v_pk_fma_f32 v[178:179], v[168:169], v[96:97], v[178:179]
	v_pk_fma_f32 v[180:181], v[162:163], v[96:97], v[180:181]
	v_pk_fma_f32 v[182:183], v[160:161], v[96:97], v[182:183]
	v_pk_fma_f32 v[184:185], v[158:159], v[96:97], v[184:185]
	v_pk_fma_f32 v[186:187], v[156:157], v[96:97], v[186:187]
	v_pk_fma_f32 v[188:189], v[154:155], v[96:97], v[188:189]
	v_pk_fma_f32 v[190:191], v[152:153], v[96:97], v[190:191]
	v_pk_fma_f32 v[78:79], v[150:151], v[96:97], v[78:79]
	v_pk_fma_f32 v[80:81], v[148:149], v[96:97], v[80:81]
	v_pk_fma_f32 v[82:83], v[146:147], v[96:97], v[82:83]
	v_pk_fma_f32 v[84:85], v[144:145], v[96:97], v[84:85]
	v_pk_fma_f32 v[86:87], v[142:143], v[96:97], v[86:87]
	v_pk_fma_f32 v[88:89], v[140:141], v[96:97], v[88:89]
	s_waitcnt vmcnt(28)
	v_lshlrev_b32_e32 v98, 16, v226
	v_and_b32_e32 v99, 0xffff0000, v226
	v_pk_fma_f32 v[178:179], v[170:171], v[98:99], v[178:179]
	v_pk_fma_f32 v[180:181], v[168:169], v[98:99], v[180:181]
	v_pk_fma_f32 v[182:183], v[162:163], v[98:99], v[182:183]
	v_pk_fma_f32 v[184:185], v[160:161], v[98:99], v[184:185]
	v_pk_fma_f32 v[186:187], v[158:159], v[98:99], v[186:187]
	v_pk_fma_f32 v[188:189], v[156:157], v[98:99], v[188:189]
	v_pk_fma_f32 v[190:191], v[154:155], v[98:99], v[190:191]
	v_pk_fma_f32 v[78:79], v[152:153], v[98:99], v[78:79]
	v_pk_fma_f32 v[80:81], v[150:151], v[98:99], v[80:81]
	v_pk_fma_f32 v[82:83], v[148:149], v[98:99], v[82:83]
	v_pk_fma_f32 v[84:85], v[146:147], v[98:99], v[84:85]
	v_pk_fma_f32 v[86:87], v[144:145], v[98:99], v[86:87]
	v_pk_fma_f32 v[88:89], v[142:143], v[98:99], v[88:89]
	s_waitcnt vmcnt(27)
	v_lshlrev_b32_e32 v96, 16, v227
	v_and_b32_e32 v97, 0xffff0000, v227
	v_pk_fma_f32 v[180:181], v[170:171], v[96:97], v[180:181]
	v_pk_fma_f32 v[182:183], v[168:169], v[96:97], v[182:183]
	v_pk_fma_f32 v[184:185], v[162:163], v[96:97], v[184:185]
	v_pk_fma_f32 v[186:187], v[160:161], v[96:97], v[186:187]
	v_pk_fma_f32 v[188:189], v[158:159], v[96:97], v[188:189]
	v_pk_fma_f32 v[190:191], v[156:157], v[96:97], v[190:191]
	v_pk_fma_f32 v[78:79], v[154:155], v[96:97], v[78:79]
	v_pk_fma_f32 v[80:81], v[152:153], v[96:97], v[80:81]
	v_pk_fma_f32 v[82:83], v[150:151], v[96:97], v[82:83]
	v_pk_fma_f32 v[84:85], v[148:149], v[96:97], v[84:85]
	v_pk_fma_f32 v[86:87], v[146:147], v[96:97], v[86:87]
	v_pk_fma_f32 v[88:89], v[144:145], v[96:97], v[88:89]
	s_waitcnt vmcnt(26)
	v_lshlrev_b32_e32 v98, 16, v228
	v_and_b32_e32 v99, 0xffff0000, v228
	v_pk_fma_f32 v[182:183], v[170:171], v[98:99], v[182:183]
	v_pk_fma_f32 v[184:185], v[168:169], v[98:99], v[184:185]
	v_pk_fma_f32 v[186:187], v[162:163], v[98:99], v[186:187]
	v_pk_fma_f32 v[188:189], v[160:161], v[98:99], v[188:189]
	v_pk_fma_f32 v[190:191], v[158:159], v[98:99], v[190:191]
	v_pk_fma_f32 v[78:79], v[156:157], v[98:99], v[78:79]
	v_pk_fma_f32 v[80:81], v[154:155], v[98:99], v[80:81]
	v_pk_fma_f32 v[82:83], v[152:153], v[98:99], v[82:83]
	v_pk_fma_f32 v[84:85], v[150:151], v[98:99], v[84:85]
	v_pk_fma_f32 v[86:87], v[148:149], v[98:99], v[86:87]
	v_pk_fma_f32 v[88:89], v[146:147], v[98:99], v[88:89]
	s_waitcnt vmcnt(25)
	v_lshlrev_b32_e32 v96, 16, v229
	v_and_b32_e32 v97, 0xffff0000, v229
	v_pk_fma_f32 v[184:185], v[170:171], v[96:97], v[184:185]
	v_pk_fma_f32 v[186:187], v[168:169], v[96:97], v[186:187]
	v_pk_fma_f32 v[188:189], v[162:163], v[96:97], v[188:189]
	v_pk_fma_f32 v[190:191], v[160:161], v[96:97], v[190:191]
	v_pk_fma_f32 v[78:79], v[158:159], v[96:97], v[78:79]
	v_pk_fma_f32 v[80:81], v[156:157], v[96:97], v[80:81]
	v_pk_fma_f32 v[82:83], v[154:155], v[96:97], v[82:83]
	v_pk_fma_f32 v[84:85], v[152:153], v[96:97], v[84:85]
	v_pk_fma_f32 v[86:87], v[150:151], v[96:97], v[86:87]
	v_pk_fma_f32 v[88:89], v[148:149], v[96:97], v[88:89]
	s_waitcnt vmcnt(24)
	v_lshlrev_b32_e32 v98, 16, v230
	v_and_b32_e32 v99, 0xffff0000, v230
	v_pk_fma_f32 v[186:187], v[170:171], v[98:99], v[186:187]
	v_pk_fma_f32 v[188:189], v[168:169], v[98:99], v[188:189]
	v_pk_fma_f32 v[190:191], v[162:163], v[98:99], v[190:191]
	v_pk_fma_f32 v[78:79], v[160:161], v[98:99], v[78:79]
	v_pk_fma_f32 v[80:81], v[158:159], v[98:99], v[80:81]
	v_pk_fma_f32 v[82:83], v[156:157], v[98:99], v[82:83]
	v_pk_fma_f32 v[84:85], v[154:155], v[98:99], v[84:85]
	v_pk_fma_f32 v[86:87], v[152:153], v[98:99], v[86:87]
	v_pk_fma_f32 v[88:89], v[150:151], v[98:99], v[88:89]
	s_waitcnt vmcnt(23)
	v_lshlrev_b32_e32 v96, 16, v231
	v_and_b32_e32 v97, 0xffff0000, v231
	v_pk_fma_f32 v[188:189], v[170:171], v[96:97], v[188:189]
	v_pk_fma_f32 v[190:191], v[168:169], v[96:97], v[190:191]
	v_pk_fma_f32 v[78:79], v[162:163], v[96:97], v[78:79]
	v_pk_fma_f32 v[80:81], v[160:161], v[96:97], v[80:81]
	v_pk_fma_f32 v[82:83], v[158:159], v[96:97], v[82:83]
	v_pk_fma_f32 v[84:85], v[156:157], v[96:97], v[84:85]
	v_pk_fma_f32 v[86:87], v[154:155], v[96:97], v[86:87]
	v_pk_fma_f32 v[88:89], v[152:153], v[96:97], v[88:89]
	s_waitcnt vmcnt(22)
	v_lshlrev_b32_e32 v98, 16, v232
	v_and_b32_e32 v99, 0xffff0000, v232
	v_pk_fma_f32 v[190:191], v[170:171], v[98:99], v[190:191]
	v_pk_fma_f32 v[78:79], v[168:169], v[98:99], v[78:79]
	v_pk_fma_f32 v[80:81], v[162:163], v[98:99], v[80:81]
	v_pk_fma_f32 v[82:83], v[160:161], v[98:99], v[82:83]
	v_pk_fma_f32 v[84:85], v[158:159], v[98:99], v[84:85]
	v_pk_fma_f32 v[86:87], v[156:157], v[98:99], v[86:87]
	v_pk_fma_f32 v[88:89], v[154:155], v[98:99], v[88:89]
	s_waitcnt vmcnt(21)
; __device__ __forceinline__ unsigned pk2(float lo, float hi) { f32x2v v = {lo, hi}; b16x2v b = __builtin_convertvector(v, b16x2v); return __builtin_bit_cast(unsigned, b); }
; __device__ __forceinline__ float fsigmoid(float x) { return __builtin_amdgcn_rcpf(1.0f + __expf(-x)); }
; template <int CTRL> __device__ __forceinline__ float dpp_mov(float v) { return __builtin_bit_cast(float, __builtin_amdgcn_update_dpp(0, __builtin_bit_cast(int, v), CTRL, 0xf, 0xf, true)); }
; __device__ __forceinline__ f32x2v bf2(unsigned v) { return (f32x2v){bflo(v), bfhi(v)}; }
; __device__ __forceinline__ float half_wave_sum(float v) {
;     v += dpp_mov<0xB1>(v);
;     v += dpp_mov<0x4E>(v);
;     v += dpp_mov<0x141>(v);
;     v += dpp_mov<0x140>(v);
;     v += __shfl_xor(v, 16);
;     return v;
; }
; __device__ __forceinline__ void gn_swish_store(float v0, float v1, f32x2v gg, f32x2v gb, unsigned* dst) {
;     const float mean = half_wave_sum(v0 + v1) * (1.0f / 64.0f); const float d0 = v0 - mean, d1 = v1 - mean;
;     const float rstd = rsqrtf(half_wave_sum(d0 * d0 + d1 * d1) * (1.0f / 64.0f) + LN_EPS);
;     float y0 = d0 * rstd * gg.x + gb.x, y1 = d1 * rstd * gg.y + gb.y;
;     y0 = y0 * fsigmoid(y0); y1 = y1 * fsigmoid(y1);
;     *dst = pk2(y0, y1);
; }
; __device__ __forceinline__ void mixer_prompt_run(const Args& p, int run, int c2) {
;     ...
;             for (int i = 0; i < 38; ++i) {
;                 const int ti = t0 + 8 * hh - 30 + i; unsigned v = U32[(rowb + (ti >= 0 ? ti : 0)) * 256 + c2]; v = (ti >= 0) ? v : 0u; const f32x2v x = bf2(v);
; #pragma unroll
;                 for (int t = 0; t < 8; ++t) { const int j = i - t; if (j >= 0 && j <= 30) a[t] = w[j] * x + a[t]; }
;                 if (i == 18) asm volatile("" ::: "memory");
	v_lshlrev_b32_e32 v96, 16, v233
	v_and_b32_e32 v97, 0xffff0000, v233
	v_pk_fma_f32 v[78:79], v[170:171], v[96:97], v[78:79]
	v_pk_fma_f32 v[80:81], v[168:169], v[96:97], v[80:81]
	v_pk_fma_f32 v[82:83], v[162:163], v[96:97], v[82:83]
	v_pk_fma_f32 v[84:85], v[160:161], v[96:97], v[84:85]
	v_pk_fma_f32 v[86:87], v[158:159], v[96:97], v[86:87]
	v_pk_fma_f32 v[88:89], v[156:157], v[96:97], v[88:89]
	s_waitcnt vmcnt(20)
	v_lshlrev_b32_e32 v98, 16, v234
	v_and_b32_e32 v99, 0xffff0000, v234
	v_pk_fma_f32 v[80:81], v[170:171], v[98:99], v[80:81]
	v_pk_fma_f32 v[82:83], v[168:169], v[98:99], v[82:83]
	v_pk_fma_f32 v[84:85], v[162:163], v[98:99], v[84:85]
	v_pk_fma_f32 v[86:87], v[160:161], v[98:99], v[86:87]
	v_pk_fma_f32 v[88:89], v[158:159], v[98:99], v[88:89]
	s_waitcnt vmcnt(19)
	v_lshlrev_b32_e32 v96, 16, v235
	v_and_b32_e32 v97, 0xffff0000, v235
	v_pk_fma_f32 v[82:83], v[170:171], v[96:97], v[82:83]
	v_pk_fma_f32 v[84:85], v[168:169], v[96:97], v[84:85]
	v_pk_fma_f32 v[86:87], v[162:163], v[96:97], v[86:87]
	v_pk_fma_f32 v[88:89], v[160:161], v[96:97], v[88:89]
	s_waitcnt vmcnt(18)
	v_lshlrev_b32_e32 v98, 16, v236
	v_and_b32_e32 v99, 0xffff0000, v236
	v_pk_fma_f32 v[84:85], v[170:171], v[98:99], v[84:85]
	v_pk_fma_f32 v[86:87], v[168:169], v[98:99], v[86:87]
	v_pk_fma_f32 v[88:89], v[162:163], v[98:99], v[88:89]
	s_waitcnt vmcnt(17)
	v_lshlrev_b32_e32 v96, 16, v237
	v_and_b32_e32 v97, 0xffff0000, v237
	v_pk_fma_f32 v[86:87], v[170:171], v[96:97], v[86:87]
	v_pk_fma_f32 v[88:89], v[168:169], v[96:97], v[88:89]
	s_waitcnt vmcnt(16)
	v_lshlrev_b32_e32 v98, 16, v238
	v_and_b32_e32 v99, 0xffff0000, v238
	v_pk_fma_f32 v[88:89], v[170:171], v[98:99], v[88:89]
	v_add_f32_e32 v106, v172, v173
	v_add_f32_e32 v110, v174, v175
	v_add_f32_e32 v114, v176, v177
	v_add_f32_e32 v118, v178, v179
	v_add_f32_e32 v122, v180, v181
	v_add_f32_e32 v126, v182, v183
	v_add_f32_e32 v130, v184, v185
	v_add_f32_e32 v134, v186, v187
	v_add_f32_dpp v106, v106, v106 quad_perm:[1,0,3,2] row_mask:0xf bank_mask:0xf bound_ctrl:1
	v_add_f32_dpp v110, v110, v110 quad_perm:[1,0,3,2] row_mask:0xf bank_mask:0xf bound_ctrl:1
	v_add_f32_dpp v114, v114, v114 quad_perm:[1,0,3,2] row_mask:0xf bank_mask:0xf bound_ctrl:1
	v_add_f32_dpp v118, v118, v118 quad_perm:[1,0,3,2] row_mask:0xf bank_mask:0xf bound_ctrl:1
	v_add_f32_dpp v122, v122, v122 quad_perm:[1,0,3,2] row_mask:0xf bank_mask:0xf bound_ctrl:1
	v_add_f32_dpp v126, v126, v126 quad_perm:[1,0,3,2] row_mask:0xf bank_mask:0xf bound_ctrl:1
	v_add_f32_dpp v130, v130, v130 quad_perm:[1,0,3,2] row_mask:0xf bank_mask:0xf bound_ctrl:1
	v_add_f32_dpp v134, v134, v134 quad_perm:[1,0,3,2] row_mask:0xf bank_mask:0xf bound_ctrl:1
	v_add_f32_dpp v106, v106, v106 quad_perm:[2,3,0,1] row_mask:0xf bank_mask:0xf bound_ctrl:1
	v_add_f32_dpp v110, v110, v110 quad_perm:[2,3,0,1] row_mask:0xf bank_mask:0xf bound_ctrl:1
	v_add_f32_dpp v114, v114, v114 quad_perm:[2,3,0,1] row_mask:0xf bank_mask:0xf bound_ctrl:1
	v_add_f32_dpp v118, v118, v118 quad_perm:[2,3,0,1] row_mask:0xf bank_mask:0xf bound_ctrl:1
	v_add_f32_dpp v122, v122, v122 quad_perm:[2,3,0,1] row_mask:0xf bank_mask:0xf bound_ctrl:1
	v_add_f32_dpp v126, v126, v126 quad_perm:[2,3,0,1] row_mask:0xf bank_mask:0xf bound_ctrl:1
	v_add_f32_dpp v130, v130, v130 quad_perm:[2,3,0,1] row_mask:0xf bank_mask:0xf bound_ctrl:1
	v_add_f32_dpp v134, v134, v134 quad_perm:[2,3,0,1] row_mask:0xf bank_mask:0xf bound_ctrl:1
	v_add_f32_dpp v106, v106, v106 row_half_mirror row_mask:0xf bank_mask:0xf bound_ctrl:1
	v_add_f32_dpp v110, v110, v110 row_half_mirror row_mask:0xf bank_mask:0xf bound_ctrl:1
	v_add_f32_dpp v114, v114, v114 row_half_mirror row_mask:0xf bank_mask:0xf bound_ctrl:1
	v_add_f32_dpp v118, v118, v118 row_half_mirror row_mask:0xf bank_mask:0xf bound_ctrl:1
	v_add_f32_dpp v122, v122, v122 row_half_mirror row_mask:0xf bank_mask:0xf bound_ctrl:1
	v_add_f32_dpp v126, v126, v126 row_half_mirror row_mask:0xf bank_mask:0xf bound_ctrl:1
	v_add_f32_dpp v130, v130, v130 row_half_mirror row_mask:0xf bank_mask:0xf bound_ctrl:1
	v_add_f32_dpp v134, v134, v134 row_half_mirror row_mask:0xf bank_mask:0xf bound_ctrl:1
	v_add_f32_dpp v106, v106, v106 row_mirror row_mask:0xf bank_mask:0xf bound_ctrl:1
	v_add_f32_dpp v110, v110, v110 row_mirror row_mask:0xf bank_mask:0xf bound_ctrl:1
	v_add_f32_dpp v114, v114, v114 row_mirror row_mask:0xf bank_mask:0xf bound_ctrl:1
	v_add_f32_dpp v118, v118, v118 row_mirror row_mask:0xf bank_mask:0xf bound_ctrl:1
	v_add_f32_dpp v122, v122, v122 row_mirror row_mask:0xf bank_mask:0xf bound_ctrl:1
	v_add_f32_dpp v126, v126, v126 row_mirror row_mask:0xf bank_mask:0xf bound_ctrl:1
	v_add_f32_dpp v130, v130, v130 row_mirror row_mask:0xf bank_mask:0xf bound_ctrl:1
	v_add_f32_dpp v134, v134, v134 row_mirror row_mask:0xf bank_mask:0xf bound_ctrl:1
	ds_bpermute_b32 v107, v239, v106
	ds_bpermute_b32 v111, v239, v110
	ds_bpermute_b32 v115, v239, v114
	ds_bpermute_b32 v119, v239, v118
	ds_bpermute_b32 v123, v239, v122
	ds_bpermute_b32 v127, v239, v126
	ds_bpermute_b32 v131, v239, v130
	ds_bpermute_b32 v135, v239, v134
	s_waitcnt lgkmcnt(7)
	v_add_f32_e32 v106, v106, v107
	s_waitcnt lgkmcnt(6)
	v_add_f32_e32 v110, v110, v111
	s_waitcnt lgkmcnt(5)
	v_add_f32_e32 v114, v114, v115
	s_waitcnt lgkmcnt(4)
	v_add_f32_e32 v118, v118, v119
	s_waitcnt lgkmcnt(3)
	v_add_f32_e32 v122, v122, v123
	s_waitcnt lgkmcnt(2)
	v_add_f32_e32 v126, v126, v127
	s_waitcnt lgkmcnt(1)
	v_add_f32_e32 v130, v130, v131
	s_waitcnt lgkmcnt(0)
; __device__ __forceinline__ unsigned pk2(float lo, float hi) { f32x2v v = {lo, hi}; b16x2v b = __builtin_convertvector(v, b16x2v); return __builtin_bit_cast(unsigned, b); }
; __device__ __forceinline__ float fsigmoid(float x) { return __builtin_amdgcn_rcpf(1.0f + __expf(-x)); }
; template <int CTRL> __device__ __forceinline__ float dpp_mov(float v) { return __builtin_bit_cast(float, __builtin_amdgcn_update_dpp(0, __builtin_bit_cast(int, v), CTRL, 0xf, 0xf, true)); }
; __device__ __forceinline__ float half_wave_sum(float v) {
;     v += dpp_mov<0xB1>(v);
;     v += dpp_mov<0x4E>(v);
;     v += dpp_mov<0x141>(v);
;     v += dpp_mov<0x140>(v);
;     v += __shfl_xor(v, 16);
;     return v;
; }
; __device__ __forceinline__ void gn_swish_store(float v0, float v1, f32x2v gg, f32x2v gb, unsigned* dst) {
;     const float mean = half_wave_sum(v0 + v1) * (1.0f / 64.0f); const float d0 = v0 - mean, d1 = v1 - mean;
;     const float rstd = rsqrtf(half_wave_sum(d0 * d0 + d1 * d1) * (1.0f / 64.0f) + LN_EPS);
;     float y0 = d0 * rstd * gg.x + gb.x, y1 = d1 * rstd * gg.y + gb.y;
;     y0 = y0 * fsigmoid(y0); y1 = y1 * fsigmoid(y1);
;     *dst = pk2(y0, y1);
; }
	v_add_f32_e32 v134, v134, v135
	v_mul_f32_e32 v106, 0x3c800000, v106
	v_mul_f32_e32 v110, 0x3c800000, v110
	v_mul_f32_e32 v114, 0x3c800000, v114
	v_mul_f32_e32 v118, 0x3c800000, v118
	v_mul_f32_e32 v122, 0x3c800000, v122
	v_mul_f32_e32 v126, 0x3c800000, v126
	v_mul_f32_e32 v130, 0x3c800000, v130
	v_mul_f32_e32 v134, 0x3c800000, v134
	v_pk_add_f32 v[172:173], v[172:173], v[106:107] op_sel_hi:[1,0] neg_lo:[0,1] neg_hi:[0,1]
	v_pk_add_f32 v[174:175], v[174:175], v[110:111] op_sel_hi:[1,0] neg_lo:[0,1] neg_hi:[0,1]
	v_pk_add_f32 v[176:177], v[176:177], v[114:115] op_sel_hi:[1,0] neg_lo:[0,1] neg_hi:[0,1]
	v_pk_add_f32 v[178:179], v[178:179], v[118:119] op_sel_hi:[1,0] neg_lo:[0,1] neg_hi:[0,1]
	v_pk_add_f32 v[180:181], v[180:181], v[122:123] op_sel_hi:[1,0] neg_lo:[0,1] neg_hi:[0,1]
	v_pk_add_f32 v[182:183], v[182:183], v[126:127] op_sel_hi:[1,0] neg_lo:[0,1] neg_hi:[0,1]
	v_pk_add_f32 v[184:185], v[184:185], v[130:131] op_sel_hi:[1,0] neg_lo:[0,1] neg_hi:[0,1]
	v_pk_add_f32 v[186:187], v[186:187], v[134:135] op_sel_hi:[1,0] neg_lo:[0,1] neg_hi:[0,1]
	v_pk_mul_f32 v[108:109], v[172:173], v[172:173]
	v_pk_mul_f32 v[112:113], v[174:175], v[174:175]
	v_pk_mul_f32 v[116:117], v[176:177], v[176:177]
	v_pk_mul_f32 v[120:121], v[178:179], v[178:179]
	v_pk_mul_f32 v[124:125], v[180:181], v[180:181]
	v_pk_mul_f32 v[128:129], v[182:183], v[182:183]
	v_pk_mul_f32 v[132:133], v[184:185], v[184:185]
	v_pk_mul_f32 v[136:137], v[186:187], v[186:187]
	v_add_f32_e32 v106, v108, v109
	v_add_f32_e32 v110, v112, v113
	v_add_f32_e32 v114, v116, v117
	v_add_f32_e32 v118, v120, v121
	v_add_f32_e32 v122, v124, v125
	v_add_f32_e32 v126, v128, v129
	v_add_f32_e32 v130, v132, v133
	v_add_f32_e32 v134, v136, v137
	v_add_f32_dpp v106, v106, v106 quad_perm:[1,0,3,2] row_mask:0xf bank_mask:0xf bound_ctrl:1
	v_add_f32_dpp v110, v110, v110 quad_perm:[1,0,3,2] row_mask:0xf bank_mask:0xf bound_ctrl:1
	v_add_f32_dpp v114, v114, v114 quad_perm:[1,0,3,2] row_mask:0xf bank_mask:0xf bound_ctrl:1
	v_add_f32_dpp v118, v118, v118 quad_perm:[1,0,3,2] row_mask:0xf bank_mask:0xf bound_ctrl:1
	v_add_f32_dpp v122, v122, v122 quad_perm:[1,0,3,2] row_mask:0xf bank_mask:0xf bound_ctrl:1
	v_add_f32_dpp v126, v126, v126 quad_perm:[1,0,3,2] row_mask:0xf bank_mask:0xf bound_ctrl:1
	v_add_f32_dpp v130, v130, v130 quad_perm:[1,0,3,2] row_mask:0xf bank_mask:0xf bound_ctrl:1
	v_add_f32_dpp v134, v134, v134 quad_perm:[1,0,3,2] row_mask:0xf bank_mask:0xf bound_ctrl:1
	v_add_f32_dpp v106, v106, v106 quad_perm:[2,3,0,1] row_mask:0xf bank_mask:0xf bound_ctrl:1
	v_add_f32_dpp v110, v110, v110 quad_perm:[2,3,0,1] row_mask:0xf bank_mask:0xf bound_ctrl:1
	v_add_f32_dpp v114, v114, v114 quad_perm:[2,3,0,1] row_mask:0xf bank_mask:0xf bound_ctrl:1
	v_add_f32_dpp v118, v118, v118 quad_perm:[2,3,0,1] row_mask:0xf bank_mask:0xf bound_ctrl:1
	v_add_f32_dpp v122, v122, v122 quad_perm:[2,3,0,1] row_mask:0xf bank_mask:0xf bound_ctrl:1
	v_add_f32_dpp v126, v126, v126 quad_perm:[2,3,0,1] row_mask:0xf bank_mask:0xf bound_ctrl:1
	v_add_f32_dpp v130, v130, v130 quad_perm:[2,3,0,1] row_mask:0xf bank_mask:0xf bound_ctrl:1
	v_add_f32_dpp v134, v134, v134 quad_perm:[2,3,0,1] row_mask:0xf bank_mask:0xf bound_ctrl:1
	v_add_f32_dpp v106, v106, v106 row_half_mirror row_mask:0xf bank_mask:0xf bound_ctrl:1
	v_add_f32_dpp v110, v110, v110 row_half_mirror row_mask:0xf bank_mask:0xf bound_ctrl:1
	v_add_f32_dpp v114, v114, v114 row_half_mirror row_mask:0xf bank_mask:0xf bound_ctrl:1
	v_add_f32_dpp v118, v118, v118 row_half_mirror row_mask:0xf bank_mask:0xf bound_ctrl:1
	v_add_f32_dpp v122, v122, v122 row_half_mirror row_mask:0xf bank_mask:0xf bound_ctrl:1
	v_add_f32_dpp v126, v126, v126 row_half_mirror row_mask:0xf bank_mask:0xf bound_ctrl:1
	v_add_f32_dpp v130, v130, v130 row_half_mirror row_mask:0xf bank_mask:0xf bound_ctrl:1
	v_add_f32_dpp v134, v134, v134 row_half_mirror row_mask:0xf bank_mask:0xf bound_ctrl:1
	v_add_f32_dpp v106, v106, v106 row_mirror row_mask:0xf bank_mask:0xf bound_ctrl:1
	v_add_f32_dpp v110, v110, v110 row_mirror row_mask:0xf bank_mask:0xf bound_ctrl:1
	v_add_f32_dpp v114, v114, v114 row_mirror row_mask:0xf bank_mask:0xf bound_ctrl:1
	v_add_f32_dpp v118, v118, v118 row_mirror row_mask:0xf bank_mask:0xf bound_ctrl:1
	v_add_f32_dpp v122, v122, v122 row_mirror row_mask:0xf bank_mask:0xf bound_ctrl:1
	v_add_f32_dpp v126, v126, v126 row_mirror row_mask:0xf bank_mask:0xf bound_ctrl:1
	v_add_f32_dpp v130, v130, v130 row_mirror row_mask:0xf bank_mask:0xf bound_ctrl:1
	v_add_f32_dpp v134, v134, v134 row_mirror row_mask:0xf bank_mask:0xf bound_ctrl:1
	ds_bpermute_b32 v107, v239, v106
	ds_bpermute_b32 v111, v239, v110
	ds_bpermute_b32 v115, v239, v114
	ds_bpermute_b32 v119, v239, v118
	ds_bpermute_b32 v123, v239, v122
	ds_bpermute_b32 v127, v239, v126
	ds_bpermute_b32 v131, v239, v130
	ds_bpermute_b32 v135, v239, v134
	s_waitcnt lgkmcnt(7)
	v_add_f32_e32 v106, v106, v107
	s_waitcnt lgkmcnt(6)
	v_add_f32_e32 v110, v110, v111
	s_waitcnt lgkmcnt(5)
	v_add_f32_e32 v114, v114, v115
	s_waitcnt lgkmcnt(4)
	v_add_f32_e32 v118, v118, v119
	s_waitcnt lgkmcnt(3)
	v_add_f32_e32 v122, v122, v123
	s_waitcnt lgkmcnt(2)
	v_add_f32_e32 v126, v126, v127
	s_waitcnt lgkmcnt(1)
	v_add_f32_e32 v130, v130, v131
	s_waitcnt lgkmcnt(0)
; __device__ __forceinline__ unsigned pk2(float lo, float hi) { f32x2v v = {lo, hi}; b16x2v b = __builtin_convertvector(v, b16x2v); return __builtin_bit_cast(unsigned, b); }
; __device__ __forceinline__ float fsigmoid(float x) { return __builtin_amdgcn_rcpf(1.0f + __expf(-x)); }
; __device__ __forceinline__ void gn_swish_store(float v0, float v1, f32x2v gg, f32x2v gb, unsigned* dst) {
;     const float mean = half_wave_sum(v0 + v1) * (1.0f / 64.0f); const float d0 = v0 - mean, d1 = v1 - mean;
;     const float rstd = rsqrtf(half_wave_sum(d0 * d0 + d1 * d1) * (1.0f / 64.0f) + LN_EPS);
;     float y0 = d0 * rstd * gg.x + gb.x, y1 = d1 * rstd * gg.y + gb.y;
;     y0 = y0 * fsigmoid(y0); y1 = y1 * fsigmoid(y1);
;     *dst = pk2(y0, y1);
; }
	v_add_f32_e32 v134, v134, v135
	v_mul_f32_e32 v106, 0x3c800000, v106
	v_mul_f32_e32 v110, 0x3c800000, v110
	v_mul_f32_e32 v114, 0x3c800000, v114
	v_mul_f32_e32 v118, 0x3c800000, v118
	v_mul_f32_e32 v122, 0x3c800000, v122
	v_mul_f32_e32 v126, 0x3c800000, v126
	v_mul_f32_e32 v130, 0x3c800000, v130
	v_mul_f32_e32 v134, 0x3c800000, v134
	v_add_f32_e32 v106, 0x3727c5ac, v106
	v_add_f32_e32 v110, 0x3727c5ac, v110
	v_add_f32_e32 v114, 0x3727c5ac, v114
	v_add_f32_e32 v118, 0x3727c5ac, v118
	v_add_f32_e32 v122, 0x3727c5ac, v122
	v_add_f32_e32 v126, 0x3727c5ac, v126
	v_add_f32_e32 v130, 0x3727c5ac, v130
	v_add_f32_e32 v134, 0x3727c5ac, v134
	v_rsq_f32_e32 v106, v106
	v_rsq_f32_e32 v110, v110
	v_rsq_f32_e32 v114, v114
	v_rsq_f32_e32 v118, v118
	v_rsq_f32_e32 v122, v122
	v_rsq_f32_e32 v126, v126
	v_rsq_f32_e32 v130, v130
	v_rsq_f32_e32 v134, v134
	v_pk_mul_f32 v[172:173], v[172:173], v[106:107] op_sel_hi:[1,0]
	v_pk_mul_f32 v[174:175], v[174:175], v[110:111] op_sel_hi:[1,0]
	v_pk_mul_f32 v[176:177], v[176:177], v[114:115] op_sel_hi:[1,0]
	v_pk_mul_f32 v[178:179], v[178:179], v[118:119] op_sel_hi:[1,0]
	v_pk_mul_f32 v[180:181], v[180:181], v[122:123] op_sel_hi:[1,0]
	v_pk_mul_f32 v[182:183], v[182:183], v[126:127] op_sel_hi:[1,0]
	v_pk_mul_f32 v[184:185], v[184:185], v[130:131] op_sel_hi:[1,0]
	v_pk_mul_f32 v[186:187], v[186:187], v[134:135] op_sel_hi:[1,0]
	v_pk_fma_f32 v[172:173], v[172:173], v[92:93], v[94:95]
	v_pk_fma_f32 v[174:175], v[174:175], v[92:93], v[94:95]
	v_pk_fma_f32 v[176:177], v[176:177], v[92:93], v[94:95]
	v_pk_fma_f32 v[178:179], v[178:179], v[92:93], v[94:95]
	v_pk_fma_f32 v[180:181], v[180:181], v[92:93], v[94:95]
	v_pk_fma_f32 v[182:183], v[182:183], v[92:93], v[94:95]
	v_pk_fma_f32 v[184:185], v[184:185], v[92:93], v[94:95]
	v_pk_fma_f32 v[186:187], v[186:187], v[92:93], v[94:95]
	v_mul_f32_e32 v108, 0xbfb8aa3b, v172
	v_mul_f32_e32 v109, 0xbfb8aa3b, v173
	v_mul_f32_e32 v112, 0xbfb8aa3b, v174
	v_mul_f32_e32 v113, 0xbfb8aa3b, v175
	v_mul_f32_e32 v116, 0xbfb8aa3b, v176
	v_mul_f32_e32 v117, 0xbfb8aa3b, v177
	v_mul_f32_e32 v120, 0xbfb8aa3b, v178
	v_mul_f32_e32 v121, 0xbfb8aa3b, v179
	v_mul_f32_e32 v124, 0xbfb8aa3b, v180
	v_mul_f32_e32 v125, 0xbfb8aa3b, v181
	v_mul_f32_e32 v128, 0xbfb8aa3b, v182
	v_mul_f32_e32 v129, 0xbfb8aa3b, v183
	v_mul_f32_e32 v132, 0xbfb8aa3b, v184
	v_mul_f32_e32 v133, 0xbfb8aa3b, v185
	v_mul_f32_e32 v136, 0xbfb8aa3b, v186
	v_mul_f32_e32 v137, 0xbfb8aa3b, v187
	v_exp_f32_e32 v108, v108
	v_exp_f32_e32 v109, v109
	v_exp_f32_e32 v112, v112
	v_exp_f32_e32 v113, v113
	v_exp_f32_e32 v116, v116
	v_exp_f32_e32 v117, v117
	v_exp_f32_e32 v120, v120
	v_exp_f32_e32 v121, v121
	v_exp_f32_e32 v124, v124
	v_exp_f32_e32 v125, v125
	v_exp_f32_e32 v128, v128
	v_exp_f32_e32 v129, v129
	v_exp_f32_e32 v132, v132
	v_exp_f32_e32 v133, v133
	v_exp_f32_e32 v136, v136
	v_exp_f32_e32 v137, v137
	v_add_f32_e32 v108, 1.0, v108
	v_add_f32_e32 v109, 1.0, v109
	v_add_f32_e32 v112, 1.0, v112
	v_add_f32_e32 v113, 1.0, v113
	v_add_f32_e32 v116, 1.0, v116
	v_add_f32_e32 v117, 1.0, v117
	v_add_f32_e32 v120, 1.0, v120
	v_add_f32_e32 v121, 1.0, v121
	v_add_f32_e32 v124, 1.0, v124
	v_add_f32_e32 v125, 1.0, v125
	v_add_f32_e32 v128, 1.0, v128
	v_add_f32_e32 v129, 1.0, v129
	v_add_f32_e32 v132, 1.0, v132
	v_add_f32_e32 v133, 1.0, v133
	v_add_f32_e32 v136, 1.0, v136
	v_add_f32_e32 v137, 1.0, v137
	v_rcp_f32_e32 v108, v108
	v_rcp_f32_e32 v109, v109
	v_rcp_f32_e32 v112, v112
	v_rcp_f32_e32 v113, v113
	v_rcp_f32_e32 v116, v116
	v_rcp_f32_e32 v117, v117
	v_rcp_f32_e32 v120, v120
	v_rcp_f32_e32 v121, v121
	v_rcp_f32_e32 v124, v124
	v_rcp_f32_e32 v125, v125
	v_rcp_f32_e32 v128, v128
	v_rcp_f32_e32 v129, v129
	v_rcp_f32_e32 v132, v132
	v_rcp_f32_e32 v133, v133
	v_rcp_f32_e32 v136, v136
	v_rcp_f32_e32 v137, v137
	v_pk_mul_f32 v[172:173], v[172:173], v[108:109]
	v_pk_mul_f32 v[174:175], v[174:175], v[112:113]
	v_pk_mul_f32 v[176:177], v[176:177], v[116:117]
	v_pk_mul_f32 v[178:179], v[178:179], v[120:121]
	v_pk_mul_f32 v[180:181], v[180:181], v[124:125]
	v_pk_mul_f32 v[182:183], v[182:183], v[128:129]
	v_pk_mul_f32 v[184:185], v[184:185], v[132:133]
	v_pk_mul_f32 v[186:187], v[186:187], v[136:137]
	v_cvt_pk_bf16_f32 v106, v172, v173
	v_cvt_pk_bf16_f32 v110, v174, v175
	v_cvt_pk_bf16_f32 v114, v176, v177
	v_cvt_pk_bf16_f32 v118, v178, v179
	v_cvt_pk_bf16_f32 v122, v180, v181
	v_cvt_pk_bf16_f32 v126, v182, v183
	v_cvt_pk_bf16_f32 v130, v184, v185
	v_cvt_pk_bf16_f32 v134, v186, v187
	global_store_dword v105, v106, s[70:71] offset:-4096
	global_store_dword v105, v110, s[70:71] offset:-2048
	global_store_dword v105, v114, s[70:71] offset:0
	global_store_dword v105, v118, s[70:71] offset:2048
	s_add_u32 s70, s70, 0x2000
	s_addc_u32 s71, s71, 0
	global_store_dword v105, v122, s[70:71] offset:-4096
	global_store_dword v105, v126, s[70:71] offset:-2048
	global_store_dword v105, v130, s[70:71] offset:0
	global_store_dword v105, v134, s[70:71] offset:2048
	v_add_f32_e32 v106, v188, v189
	v_add_f32_e32 v110, v190, v191
	v_add_f32_e32 v114, v78, v79
	v_add_f32_e32 v118, v80, v81
	v_add_f32_e32 v122, v82, v83
	v_add_f32_e32 v126, v84, v85
	v_add_f32_e32 v130, v86, v87
	v_add_f32_e32 v134, v88, v89
	v_add_f32_dpp v106, v106, v106 quad_perm:[1,0,3,2] row_mask:0xf bank_mask:0xf bound_ctrl:1
	v_add_f32_dpp v110, v110, v110 quad_perm:[1,0,3,2] row_mask:0xf bank_mask:0xf bound_ctrl:1
	v_add_f32_dpp v114, v114, v114 quad_perm:[1,0,3,2] row_mask:0xf bank_mask:0xf bound_ctrl:1
	v_add_f32_dpp v118, v118, v118 quad_perm:[1,0,3,2] row_mask:0xf bank_mask:0xf bound_ctrl:1
	v_add_f32_dpp v122, v122, v122 quad_perm:[1,0,3,2] row_mask:0xf bank_mask:0xf bound_ctrl:1
; __device__ __forceinline__ unsigned pk2(float lo, float hi) { f32x2v v = {lo, hi}; b16x2v b = __builtin_convertvector(v, b16x2v); return __builtin_bit_cast(unsigned, b); }
; __device__ __forceinline__ float fsigmoid(float x) { return __builtin_amdgcn_rcpf(1.0f + __expf(-x)); }
; template <int CTRL> __device__ __forceinline__ float dpp_mov(float v) { return __builtin_bit_cast(float, __builtin_amdgcn_update_dpp(0, __builtin_bit_cast(int, v), CTRL, 0xf, 0xf, true)); }
; __device__ __forceinline__ float half_wave_sum(float v) {
;     v += dpp_mov<0xB1>(v);
;     v += dpp_mov<0x4E>(v);
;     v += dpp_mov<0x141>(v);
;     v += dpp_mov<0x140>(v);
;     v += __shfl_xor(v, 16);
;     return v;
; }
; __device__ __forceinline__ void gn_swish_store(float v0, float v1, f32x2v gg, f32x2v gb, unsigned* dst) {
;     const float mean = half_wave_sum(v0 + v1) * (1.0f / 64.0f); const float d0 = v0 - mean, d1 = v1 - mean;
;     const float rstd = rsqrtf(half_wave_sum(d0 * d0 + d1 * d1) * (1.0f / 64.0f) + LN_EPS);
;     float y0 = d0 * rstd * gg.x + gb.x, y1 = d1 * rstd * gg.y + gb.y;
;     y0 = y0 * fsigmoid(y0); y1 = y1 * fsigmoid(y1);
;     *dst = pk2(y0, y1);
; }
	v_add_f32_dpp v126, v126, v126 quad_perm:[1,0,3,2] row_mask:0xf bank_mask:0xf bound_ctrl:1
	v_add_f32_dpp v130, v130, v130 quad_perm:[1,0,3,2] row_mask:0xf bank_mask:0xf bound_ctrl:1
	v_add_f32_dpp v134, v134, v134 quad_perm:[1,0,3,2] row_mask:0xf bank_mask:0xf bound_ctrl:1
	v_add_f32_dpp v106, v106, v106 quad_perm:[2,3,0,1] row_mask:0xf bank_mask:0xf bound_ctrl:1
	v_add_f32_dpp v110, v110, v110 quad_perm:[2,3,0,1] row_mask:0xf bank_mask:0xf bound_ctrl:1
	v_add_f32_dpp v114, v114, v114 quad_perm:[2,3,0,1] row_mask:0xf bank_mask:0xf bound_ctrl:1
	v_add_f32_dpp v118, v118, v118 quad_perm:[2,3,0,1] row_mask:0xf bank_mask:0xf bound_ctrl:1
	v_add_f32_dpp v122, v122, v122 quad_perm:[2,3,0,1] row_mask:0xf bank_mask:0xf bound_ctrl:1
	v_add_f32_dpp v126, v126, v126 quad_perm:[2,3,0,1] row_mask:0xf bank_mask:0xf bound_ctrl:1
	v_add_f32_dpp v130, v130, v130 quad_perm:[2,3,0,1] row_mask:0xf bank_mask:0xf bound_ctrl:1
	v_add_f32_dpp v134, v134, v134 quad_perm:[2,3,0,1] row_mask:0xf bank_mask:0xf bound_ctrl:1
	v_add_f32_dpp v106, v106, v106 row_half_mirror row_mask:0xf bank_mask:0xf bound_ctrl:1
	v_add_f32_dpp v110, v110, v110 row_half_mirror row_mask:0xf bank_mask:0xf bound_ctrl:1
	v_add_f32_dpp v114, v114, v114 row_half_mirror row_mask:0xf bank_mask:0xf bound_ctrl:1
	v_add_f32_dpp v118, v118, v118 row_half_mirror row_mask:0xf bank_mask:0xf bound_ctrl:1
	v_add_f32_dpp v122, v122, v122 row_half_mirror row_mask:0xf bank_mask:0xf bound_ctrl:1
	v_add_f32_dpp v126, v126, v126 row_half_mirror row_mask:0xf bank_mask:0xf bound_ctrl:1
	v_add_f32_dpp v130, v130, v130 row_half_mirror row_mask:0xf bank_mask:0xf bound_ctrl:1
	v_add_f32_dpp v134, v134, v134 row_half_mirror row_mask:0xf bank_mask:0xf bound_ctrl:1
	v_add_f32_dpp v106, v106, v106 row_mirror row_mask:0xf bank_mask:0xf bound_ctrl:1
	v_add_f32_dpp v110, v110, v110 row_mirror row_mask:0xf bank_mask:0xf bound_ctrl:1
	v_add_f32_dpp v114, v114, v114 row_mirror row_mask:0xf bank_mask:0xf bound_ctrl:1
	v_add_f32_dpp v118, v118, v118 row_mirror row_mask:0xf bank_mask:0xf bound_ctrl:1
	v_add_f32_dpp v122, v122, v122 row_mirror row_mask:0xf bank_mask:0xf bound_ctrl:1
	v_add_f32_dpp v126, v126, v126 row_mirror row_mask:0xf bank_mask:0xf bound_ctrl:1
	v_add_f32_dpp v130, v130, v130 row_mirror row_mask:0xf bank_mask:0xf bound_ctrl:1
	v_add_f32_dpp v134, v134, v134 row_mirror row_mask:0xf bank_mask:0xf bound_ctrl:1
	ds_bpermute_b32 v107, v239, v106
	ds_bpermute_b32 v111, v239, v110
	ds_bpermute_b32 v115, v239, v114
	ds_bpermute_b32 v119, v239, v118
	ds_bpermute_b32 v123, v239, v122
	ds_bpermute_b32 v127, v239, v126
	ds_bpermute_b32 v131, v239, v130
	ds_bpermute_b32 v135, v239, v134
	s_waitcnt lgkmcnt(7)
	v_add_f32_e32 v106, v106, v107
	s_waitcnt lgkmcnt(6)
	v_add_f32_e32 v110, v110, v111
	s_waitcnt lgkmcnt(5)
	v_add_f32_e32 v114, v114, v115
	s_waitcnt lgkmcnt(4)
	v_add_f32_e32 v118, v118, v119
	s_waitcnt lgkmcnt(3)
	v_add_f32_e32 v122, v122, v123
	s_waitcnt lgkmcnt(2)
	v_add_f32_e32 v126, v126, v127
	s_waitcnt lgkmcnt(1)
	v_add_f32_e32 v130, v130, v131
	s_waitcnt lgkmcnt(0)
	v_add_f32_e32 v134, v134, v135
	v_mul_f32_e32 v106, 0x3c800000, v106
	v_mul_f32_e32 v110, 0x3c800000, v110
	v_mul_f32_e32 v114, 0x3c800000, v114
	v_mul_f32_e32 v118, 0x3c800000, v118
	v_mul_f32_e32 v122, 0x3c800000, v122
	v_mul_f32_e32 v126, 0x3c800000, v126
	v_mul_f32_e32 v130, 0x3c800000, v130
	v_mul_f32_e32 v134, 0x3c800000, v134
	v_pk_add_f32 v[188:189], v[188:189], v[106:107] op_sel_hi:[1,0] neg_lo:[0,1] neg_hi:[0,1]
	v_pk_add_f32 v[190:191], v[190:191], v[110:111] op_sel_hi:[1,0] neg_lo:[0,1] neg_hi:[0,1]
	v_pk_add_f32 v[78:79], v[78:79], v[114:115] op_sel_hi:[1,0] neg_lo:[0,1] neg_hi:[0,1]
	v_pk_add_f32 v[80:81], v[80:81], v[118:119] op_sel_hi:[1,0] neg_lo:[0,1] neg_hi:[0,1]
	v_pk_add_f32 v[82:83], v[82:83], v[122:123] op_sel_hi:[1,0] neg_lo:[0,1] neg_hi:[0,1]
	v_pk_add_f32 v[84:85], v[84:85], v[126:127] op_sel_hi:[1,0] neg_lo:[0,1] neg_hi:[0,1]
	v_pk_add_f32 v[86:87], v[86:87], v[130:131] op_sel_hi:[1,0] neg_lo:[0,1] neg_hi:[0,1]
	v_pk_add_f32 v[88:89], v[88:89], v[134:135] op_sel_hi:[1,0] neg_lo:[0,1] neg_hi:[0,1]
	v_pk_mul_f32 v[108:109], v[188:189], v[188:189]
	v_pk_mul_f32 v[112:113], v[190:191], v[190:191]
	v_pk_mul_f32 v[116:117], v[78:79], v[78:79]
	v_pk_mul_f32 v[120:121], v[80:81], v[80:81]
	v_pk_mul_f32 v[124:125], v[82:83], v[82:83]
	v_pk_mul_f32 v[128:129], v[84:85], v[84:85]
	v_pk_mul_f32 v[132:133], v[86:87], v[86:87]
	v_pk_mul_f32 v[136:137], v[88:89], v[88:89]
	v_add_f32_e32 v106, v108, v109
	v_add_f32_e32 v110, v112, v113
	v_add_f32_e32 v114, v116, v117
	v_add_f32_e32 v118, v120, v121
	v_add_f32_e32 v122, v124, v125
	v_add_f32_e32 v126, v128, v129
	v_add_f32_e32 v130, v132, v133
	v_add_f32_e32 v134, v136, v137
	v_add_f32_dpp v106, v106, v106 quad_perm:[1,0,3,2] row_mask:0xf bank_mask:0xf bound_ctrl:1
	v_add_f32_dpp v110, v110, v110 quad_perm:[1,0,3,2] row_mask:0xf bank_mask:0xf bound_ctrl:1
	v_add_f32_dpp v114, v114, v114 quad_perm:[1,0,3,2] row_mask:0xf bank_mask:0xf bound_ctrl:1
	v_add_f32_dpp v118, v118, v118 quad_perm:[1,0,3,2] row_mask:0xf bank_mask:0xf bound_ctrl:1
	v_add_f32_dpp v122, v122, v122 quad_perm:[1,0,3,2] row_mask:0xf bank_mask:0xf bound_ctrl:1
	v_add_f32_dpp v126, v126, v126 quad_perm:[1,0,3,2] row_mask:0xf bank_mask:0xf bound_ctrl:1
	v_add_f32_dpp v130, v130, v130 quad_perm:[1,0,3,2] row_mask:0xf bank_mask:0xf bound_ctrl:1
	v_add_f32_dpp v134, v134, v134 quad_perm:[1,0,3,2] row_mask:0xf bank_mask:0xf bound_ctrl:1
	v_add_f32_dpp v106, v106, v106 quad_perm:[2,3,0,1] row_mask:0xf bank_mask:0xf bound_ctrl:1
	v_add_f32_dpp v110, v110, v110 quad_perm:[2,3,0,1] row_mask:0xf bank_mask:0xf bound_ctrl:1
; __device__ __forceinline__ unsigned pk2(float lo, float hi) { f32x2v v = {lo, hi}; b16x2v b = __builtin_convertvector(v, b16x2v); return __builtin_bit_cast(unsigned, b); }
; __device__ __forceinline__ float fsigmoid(float x) { return __builtin_amdgcn_rcpf(1.0f + __expf(-x)); }
; template <int CTRL> __device__ __forceinline__ float dpp_mov(float v) { return __builtin_bit_cast(float, __builtin_amdgcn_update_dpp(0, __builtin_bit_cast(int, v), CTRL, 0xf, 0xf, true)); }
; __device__ __forceinline__ float half_wave_sum(float v) {
;     v += dpp_mov<0xB1>(v);
;     v += dpp_mov<0x4E>(v);
;     v += dpp_mov<0x141>(v);
;     v += dpp_mov<0x140>(v);
;     v += __shfl_xor(v, 16);
;     return v;
; }
; __device__ __forceinline__ void gn_swish_store(float v0, float v1, f32x2v gg, f32x2v gb, unsigned* dst) {
;     const float mean = half_wave_sum(v0 + v1) * (1.0f / 64.0f); const float d0 = v0 - mean, d1 = v1 - mean;
;     const float rstd = rsqrtf(half_wave_sum(d0 * d0 + d1 * d1) * (1.0f / 64.0f) + LN_EPS);
;     float y0 = d0 * rstd * gg.x + gb.x, y1 = d1 * rstd * gg.y + gb.y;
;     y0 = y0 * fsigmoid(y0); y1 = y1 * fsigmoid(y1);
;     *dst = pk2(y0, y1);
; }
	v_add_f32_dpp v114, v114, v114 quad_perm:[2,3,0,1] row_mask:0xf bank_mask:0xf bound_ctrl:1
	v_add_f32_dpp v118, v118, v118 quad_perm:[2,3,0,1] row_mask:0xf bank_mask:0xf bound_ctrl:1
	v_add_f32_dpp v122, v122, v122 quad_perm:[2,3,0,1] row_mask:0xf bank_mask:0xf bound_ctrl:1
	v_add_f32_dpp v126, v126, v126 quad_perm:[2,3,0,1] row_mask:0xf bank_mask:0xf bound_ctrl:1
	v_add_f32_dpp v130, v130, v130 quad_perm:[2,3,0,1] row_mask:0xf bank_mask:0xf bound_ctrl:1
	v_add_f32_dpp v134, v134, v134 quad_perm:[2,3,0,1] row_mask:0xf bank_mask:0xf bound_ctrl:1
	v_add_f32_dpp v106, v106, v106 row_half_mirror row_mask:0xf bank_mask:0xf bound_ctrl:1
	v_add_f32_dpp v110, v110, v110 row_half_mirror row_mask:0xf bank_mask:0xf bound_ctrl:1
	v_add_f32_dpp v114, v114, v114 row_half_mirror row_mask:0xf bank_mask:0xf bound_ctrl:1
	v_add_f32_dpp v118, v118, v118 row_half_mirror row_mask:0xf bank_mask:0xf bound_ctrl:1
	v_add_f32_dpp v122, v122, v122 row_half_mirror row_mask:0xf bank_mask:0xf bound_ctrl:1
	v_add_f32_dpp v126, v126, v126 row_half_mirror row_mask:0xf bank_mask:0xf bound_ctrl:1
	v_add_f32_dpp v130, v130, v130 row_half_mirror row_mask:0xf bank_mask:0xf bound_ctrl:1
	v_add_f32_dpp v134, v134, v134 row_half_mirror row_mask:0xf bank_mask:0xf bound_ctrl:1
	v_add_f32_dpp v106, v106, v106 row_mirror row_mask:0xf bank_mask:0xf bound_ctrl:1
	v_add_f32_dpp v110, v110, v110 row_mirror row_mask:0xf bank_mask:0xf bound_ctrl:1
	v_add_f32_dpp v114, v114, v114 row_mirror row_mask:0xf bank_mask:0xf bound_ctrl:1
	v_add_f32_dpp v118, v118, v118 row_mirror row_mask:0xf bank_mask:0xf bound_ctrl:1
	v_add_f32_dpp v122, v122, v122 row_mirror row_mask:0xf bank_mask:0xf bound_ctrl:1
	v_add_f32_dpp v126, v126, v126 row_mirror row_mask:0xf bank_mask:0xf bound_ctrl:1
	v_add_f32_dpp v130, v130, v130 row_mirror row_mask:0xf bank_mask:0xf bound_ctrl:1
	v_add_f32_dpp v134, v134, v134 row_mirror row_mask:0xf bank_mask:0xf bound_ctrl:1
	ds_bpermute_b32 v107, v239, v106
	ds_bpermute_b32 v111, v239, v110
	ds_bpermute_b32 v115, v239, v114
	ds_bpermute_b32 v119, v239, v118
	ds_bpermute_b32 v123, v239, v122
	ds_bpermute_b32 v127, v239, v126
	ds_bpermute_b32 v131, v239, v130
	ds_bpermute_b32 v135, v239, v134
	s_waitcnt lgkmcnt(7)
	v_add_f32_e32 v106, v106, v107
	s_waitcnt lgkmcnt(6)
	v_add_f32_e32 v110, v110, v111
	s_waitcnt lgkmcnt(5)
	v_add_f32_e32 v114, v114, v115
	s_waitcnt lgkmcnt(4)
	v_add_f32_e32 v118, v118, v119
	s_waitcnt lgkmcnt(3)
	v_add_f32_e32 v122, v122, v123
	s_waitcnt lgkmcnt(2)
	v_add_f32_e32 v126, v126, v127
	s_waitcnt lgkmcnt(1)
	v_add_f32_e32 v130, v130, v131
	s_waitcnt lgkmcnt(0)
	v_add_f32_e32 v134, v134, v135
	v_mul_f32_e32 v106, 0x3c800000, v106
	v_mul_f32_e32 v110, 0x3c800000, v110
	v_mul_f32_e32 v114, 0x3c800000, v114
	v_mul_f32_e32 v118, 0x3c800000, v118
	v_mul_f32_e32 v122, 0x3c800000, v122
	v_mul_f32_e32 v126, 0x3c800000, v126
	v_mul_f32_e32 v130, 0x3c800000, v130
	v_mul_f32_e32 v134, 0x3c800000, v134
	v_add_f32_e32 v106, 0x3727c5ac, v106
	v_add_f32_e32 v110, 0x3727c5ac, v110
	v_add_f32_e32 v114, 0x3727c5ac, v114
	v_add_f32_e32 v118, 0x3727c5ac, v118
	v_add_f32_e32 v122, 0x3727c5ac, v122
	v_add_f32_e32 v126, 0x3727c5ac, v126
	v_add_f32_e32 v130, 0x3727c5ac, v130
	v_add_f32_e32 v134, 0x3727c5ac, v134
	v_rsq_f32_e32 v106, v106
	v_rsq_f32_e32 v110, v110
	v_rsq_f32_e32 v114, v114
	v_rsq_f32_e32 v118, v118
	v_rsq_f32_e32 v122, v122
	v_rsq_f32_e32 v126, v126
	v_rsq_f32_e32 v130, v130
	v_rsq_f32_e32 v134, v134
	v_pk_mul_f32 v[188:189], v[188:189], v[106:107] op_sel_hi:[1,0]
	v_pk_mul_f32 v[190:191], v[190:191], v[110:111] op_sel_hi:[1,0]
	v_pk_mul_f32 v[78:79], v[78:79], v[114:115] op_sel_hi:[1,0]
	v_pk_mul_f32 v[80:81], v[80:81], v[118:119] op_sel_hi:[1,0]
	v_pk_mul_f32 v[82:83], v[82:83], v[122:123] op_sel_hi:[1,0]
	v_pk_mul_f32 v[84:85], v[84:85], v[126:127] op_sel_hi:[1,0]
	v_pk_mul_f32 v[86:87], v[86:87], v[130:131] op_sel_hi:[1,0]
	v_pk_mul_f32 v[88:89], v[88:89], v[134:135] op_sel_hi:[1,0]
	v_pk_fma_f32 v[188:189], v[188:189], v[92:93], v[94:95]
	v_pk_fma_f32 v[190:191], v[190:191], v[92:93], v[94:95]
	v_pk_fma_f32 v[78:79], v[78:79], v[92:93], v[94:95]
	v_pk_fma_f32 v[80:81], v[80:81], v[92:93], v[94:95]
	v_pk_fma_f32 v[82:83], v[82:83], v[92:93], v[94:95]
	v_pk_fma_f32 v[84:85], v[84:85], v[92:93], v[94:95]
	v_pk_fma_f32 v[86:87], v[86:87], v[92:93], v[94:95]
	v_pk_fma_f32 v[88:89], v[88:89], v[92:93], v[94:95]
	v_mul_f32_e32 v108, 0xbfb8aa3b, v188
	v_mul_f32_e32 v109, 0xbfb8aa3b, v189
	v_mul_f32_e32 v112, 0xbfb8aa3b, v190
	v_mul_f32_e32 v113, 0xbfb8aa3b, v191
	v_mul_f32_e32 v116, 0xbfb8aa3b, v78
	v_mul_f32_e32 v117, 0xbfb8aa3b, v79
	v_mul_f32_e32 v120, 0xbfb8aa3b, v80
	v_mul_f32_e32 v121, 0xbfb8aa3b, v81
	v_mul_f32_e32 v124, 0xbfb8aa3b, v82
	v_mul_f32_e32 v125, 0xbfb8aa3b, v83
	v_mul_f32_e32 v128, 0xbfb8aa3b, v84
	v_mul_f32_e32 v129, 0xbfb8aa3b, v85
	v_mul_f32_e32 v132, 0xbfb8aa3b, v86
	v_mul_f32_e32 v133, 0xbfb8aa3b, v87
	v_mul_f32_e32 v136, 0xbfb8aa3b, v88
	v_mul_f32_e32 v137, 0xbfb8aa3b, v89
	v_exp_f32_e32 v108, v108
	v_exp_f32_e32 v109, v109
	v_exp_f32_e32 v112, v112
	v_exp_f32_e32 v113, v113
	v_exp_f32_e32 v116, v116
	v_exp_f32_e32 v117, v117
	v_exp_f32_e32 v120, v120
	v_exp_f32_e32 v121, v121
	v_exp_f32_e32 v124, v124
	v_exp_f32_e32 v125, v125
	v_exp_f32_e32 v128, v128
	v_exp_f32_e32 v129, v129
	v_exp_f32_e32 v132, v132
	v_exp_f32_e32 v133, v133
	v_exp_f32_e32 v136, v136
	v_exp_f32_e32 v137, v137
; __device__ __forceinline__ unsigned pk2(float lo, float hi) { f32x2v v = {lo, hi}; b16x2v b = __builtin_convertvector(v, b16x2v); return __builtin_bit_cast(unsigned, b); }
; __device__ __forceinline__ float fsigmoid(float x) { return __builtin_amdgcn_rcpf(1.0f + __expf(-x)); }
; __device__ __forceinline__ f32x2v bf2(unsigned v) { return (f32x2v){bflo(v), bfhi(v)}; }
; __device__ __forceinline__ void gn_swish_store(float v0, float v1, f32x2v gg, f32x2v gb, unsigned* dst) {
;     ...
;     float y0 = d0 * rstd * gg.x + gb.x, y1 = d1 * rstd * gg.y + gb.y;
;     y0 = y0 * fsigmoid(y0); y1 = y1 * fsigmoid(y1);
;     *dst = pk2(y0, y1);
; }
; __device__ __forceinline__ void mixer_prompt_run(const Args& p, int run, int c2) {
;     ...
;         unsigned pin[31];
; #pragma unroll
;         for (int i = 0; i < 31; ++i) { const int t = t0 - 15 + i; const unsigned v = P32[(rowb + (t >= 0 ? t : 0)) * 256 + c2]; pin[i] = (t >= 0) ? v : 0u; }
;     ...
;                 const int ti = t0 + 8 * hh - 30 + i; unsigned v = U32[(rowb + (ti >= 0 ? ti : 0)) * 256 + c2]; v = (ti >= 0) ? v : 0u; const f32x2v x = bf2(v);
; __device__ __forceinline__ void p2_mixer(const Args& p, int G, int bid, int tid) {
;     const int half = __builtin_amdgcn_readfirstlane(tid >> 8), c2 = tid & 255;
;     const int vcu = (G % 8 == 0) ? (bid % 8) * (G / 8) + bid / 8 : bid;
;     for (int it = vcu; it < 512 + 64; it += G) {
;         if (it < 512) mixer_prompt_run(p, 2 * it + half, c2);
	v_add_f32_e32 v108, 1.0, v108
	v_add_f32_e32 v109, 1.0, v109
	v_add_f32_e32 v112, 1.0, v112
	v_add_f32_e32 v113, 1.0, v113
	v_add_f32_e32 v116, 1.0, v116
	v_add_f32_e32 v117, 1.0, v117
	v_add_f32_e32 v120, 1.0, v120
	v_add_f32_e32 v121, 1.0, v121
	v_add_f32_e32 v124, 1.0, v124
	v_add_f32_e32 v125, 1.0, v125
	v_add_f32_e32 v128, 1.0, v128
	v_add_f32_e32 v129, 1.0, v129
	v_add_f32_e32 v132, 1.0, v132
	v_add_f32_e32 v133, 1.0, v133
	v_add_f32_e32 v136, 1.0, v136
	v_add_f32_e32 v137, 1.0, v137
	v_rcp_f32_e32 v108, v108
	v_rcp_f32_e32 v109, v109
	v_rcp_f32_e32 v112, v112
	v_rcp_f32_e32 v113, v113
	v_rcp_f32_e32 v116, v116
	v_rcp_f32_e32 v117, v117
	v_rcp_f32_e32 v120, v120
	v_rcp_f32_e32 v121, v121
	v_rcp_f32_e32 v124, v124
	v_rcp_f32_e32 v125, v125
	v_rcp_f32_e32 v128, v128
	v_rcp_f32_e32 v129, v129
	v_rcp_f32_e32 v132, v132
	v_rcp_f32_e32 v133, v133
	v_rcp_f32_e32 v136, v136
	v_rcp_f32_e32 v137, v137
	v_pk_mul_f32 v[188:189], v[188:189], v[108:109]
	v_pk_mul_f32 v[190:191], v[190:191], v[112:113]
	v_pk_mul_f32 v[78:79], v[78:79], v[116:117]
	v_pk_mul_f32 v[80:81], v[80:81], v[120:121]
	v_pk_mul_f32 v[82:83], v[82:83], v[124:125]
	v_pk_mul_f32 v[84:85], v[84:85], v[128:129]
	v_pk_mul_f32 v[86:87], v[86:87], v[132:133]
	v_pk_mul_f32 v[88:89], v[88:89], v[136:137]
	v_cvt_pk_bf16_f32 v106, v188, v189
	v_cvt_pk_bf16_f32 v110, v190, v191
	v_cvt_pk_bf16_f32 v114, v78, v79
	v_cvt_pk_bf16_f32 v118, v80, v81
	v_cvt_pk_bf16_f32 v122, v82, v83
	v_cvt_pk_bf16_f32 v126, v84, v85
	v_cvt_pk_bf16_f32 v130, v86, v87
	v_cvt_pk_bf16_f32 v134, v88, v89
	s_add_u32 s70, s70, 0x2000
	s_addc_u32 s71, s71, 0
	global_store_dword v105, v106, s[70:71] offset:-4096
	global_store_dword v105, v110, s[70:71] offset:-2048
	global_store_dword v105, v114, s[70:71] offset:0
	global_store_dword v105, v118, s[70:71] offset:2048
	s_add_u32 s70, s70, 0x2000
	s_addc_u32 s71, s71, 0
	global_store_dword v105, v122, s[70:71] offset:-4096
	global_store_dword v105, v126, s[70:71] offset:-2048
	global_store_dword v105, v130, s[70:71] offset:0
	global_store_dword v105, v134, s[70:71] offset:2048
	s_add_i32 s0, s40, s96
	s_cmpk_lt_i32 s0, 0x200
	s_cbranch_scc0 .Lmx_done
	s_lshl_b32 s0, s0, 1
	s_add_i32 s81, s0, s41
	s_lshr_b32 s63, s81, 7
	s_and_b32 s1, s81, 0x7f
	s_lshl_b32 s1, s1, 4
	s_lshl_b32 s63, s63, 11
	s_add_i32 s63, s63, s1
	s_sub_i32 s1, s63, 15
	s_lshl_b32 s65, s1, 10
	s_ashr_i32 s0, s65, 31
	s_add_u32 s68, s58, s65
	s_addc_u32 s69, s59, s0
	s_add_u32 s68, s68, 0x5d81000
	s_addc_u32 s69, s69, 0
	s_sub_i32 s1, s63, 30
	s_lshl_b32 s65, s1, 10
	s_ashr_i32 s0, s65, 31
	s_add_u32 s66, s58, s65
	s_addc_u32 s67, s59, s0
	s_add_u32 s66, s66, 0x4d01000
	s_addc_u32 s67, s67, 0
	s_waitcnt vmcnt(16)
	global_load_dword v172, v105, s[68:69] offset:-4096
	global_load_dword v173, v105, s[68:69] offset:-3072
	global_load_dword v174, v105, s[68:69] offset:-2048
	global_load_dword v175, v105, s[68:69] offset:-1024
	global_load_dword v176, v105, s[68:69] offset:0
	global_load_dword v177, v105, s[68:69] offset:1024
	global_load_dword v178, v105, s[68:69] offset:2048
	global_load_dword v179, v105, s[68:69] offset:3072
	s_add_u32 s68, s68, 0x2000
	s_addc_u32 s69, s69, 0
	global_load_dword v180, v105, s[68:69] offset:-4096
	global_load_dword v181, v105, s[68:69] offset:-3072
	global_load_dword v182, v105, s[68:69] offset:-2048
	global_load_dword v183, v105, s[68:69] offset:-1024
	global_load_dword v184, v105, s[68:69] offset:0
	global_load_dword v185, v105, s[68:69] offset:1024
	global_load_dword v186, v105, s[68:69] offset:2048
	global_load_dword v187, v105, s[68:69] offset:3072
	s_add_u32 s68, s68, 0x2000
	s_addc_u32 s69, s69, 0
	global_load_dword v188, v105, s[68:69] offset:-4096
	global_load_dword v189, v105, s[68:69] offset:-3072
	global_load_dword v190, v105, s[68:69] offset:-2048
	global_load_dword v191, v105, s[68:69] offset:-1024
	global_load_dword v78, v105, s[68:69] offset:0
	global_load_dword v79, v105, s[68:69] offset:1024
	global_load_dword v80, v105, s[68:69] offset:2048
	global_load_dword v81, v105, s[68:69] offset:3072
	s_add_u32 s68, s68, 0x2000
	s_addc_u32 s69, s69, 0
	global_load_dword v82, v105, s[68:69] offset:-4096
	global_load_dword v83, v105, s[68:69] offset:-3072
	global_load_dword v84, v105, s[68:69] offset:-2048
	global_load_dword v85, v105, s[68:69] offset:-1024
	global_load_dword v86, v105, s[68:69] offset:0
	global_load_dword v87, v105, s[68:69] offset:1024
	global_load_dword v88, v105, s[68:69] offset:2048
	global_load_dword v193, v105, s[66:67] offset:-4096
	global_load_dword v194, v105, s[66:67] offset:-3072
	global_load_dword v195, v105, s[66:67] offset:-2048
	global_load_dword v196, v105, s[66:67] offset:-1024
	global_load_dword v197, v105, s[66:67] offset:0
	global_load_dword v198, v105, s[66:67] offset:1024
	global_load_dword v199, v105, s[66:67] offset:2048
	global_load_dword v200, v105, s[66:67] offset:3072
	s_add_u32 s66, s66, 0x2000
	s_addc_u32 s67, s67, 0
	global_load_dword v201, v105, s[66:67] offset:-4096
	global_load_dword v202, v105, s[66:67] offset:-3072
	global_load_dword v203, v105, s[66:67] offset:-2048
	global_load_dword v204, v105, s[66:67] offset:-1024
	global_load_dword v205, v105, s[66:67] offset:0
	global_load_dword v206, v105, s[66:67] offset:1024
	global_load_dword v207, v105, s[66:67] offset:2048
	global_load_dword v208, v105, s[66:67] offset:3072
	s_mov_b32 s80, 1
	s_branch .Lmx_done
